# conv row norm: wave sum on the DPP network instead of six ds_bpermute round trips
# baseline (speedup 1.0000x reference)
; __device__ __forceinline__ unsigned cvt_pk_bf16(float lo, float hi) { unsigned r; asm volatile("v_cvt_pk_bf16_f32 %0, %1, %2" : "=v"(r) : "v"(lo), "v"(hi)); return r; }
; __device__ __forceinline__ float bf_lo(unsigned w) { return __uint_as_float(w << 16); }
; __device__ __forceinline__ float bf_hi(unsigned w) { return __uint_as_float(w & 0xffff0000u); }
; __device__ __forceinline__ float wave_sum(float v) {
; #pragma unroll
;     for (int o = 1; o < 64; o <<= 1) v += __shfl_xor(v, o);
;     return v;
; __global__ void __launch_bounds__(512, 2) trunk_fwd(Args args) {
;     ...
;                     float cv[8], uu[8]; float ss = 0.f;
; #pragma unroll
;                     for (int i = 0; i < 4; ++i) {
;                         uu[2 * i] = bf_lo(gu[i]); uu[2 * i + 1] = bf_hi(gu[i]);
;                         cv[2 * i] = bf_lo(gb[i]) * (w0[2 * i] * uu[2 * i] + w1[2 * i] * u1[2 * i] + w2[2 * i] * u2[2 * i]);
;                         cv[2 * i + 1] = bf_hi(gb[i]) * (w0[2 * i + 1] * uu[2 * i + 1] + w1[2 * i + 1] * u1[2 * i + 1] + w2[2 * i + 1] * u2[2 * i + 1]);
;                     }
; #pragma unroll
;                     for (int i = 0; i < 8; ++i) { ss += cv[i] * cv[i]; u2[i] = u1[i]; u1[i] = uu[i]; }
;                     ss = wave_sum(ss);
;                     const float rc = rsqrtf(ss * (1.0f / 512.0f) + EPS);
;                     u32x4 oc;
; #pragma unroll
;                     for (int i = 0; i < 4; ++i) oc[i] = cvt_pk_bf16(cv[2 * i] * rc, cv[2 * i + 1] * rc);
;                     *(u32x4*)(MIX + (size_t)r * 1024 + 512 + c0) = oc;
.Lcv_taps_ok:
	v_mad_i64_i32 v[152:153], vcc, s41, v221, v[58:59]
	s_add_u32 s41, s41, 1
	global_load_dwordx4 v[2:5], v[152:153], off offset:1536
	global_load_dwordx4 v[18:21], v[152:153], off offset:2560
	v_mad_i64_i32 v[152:153], vcc, s41, v221, v[58:59]
	s_add_u32 s41, s41, 1
	global_load_dwordx4 v[6:9], v[152:153], off offset:1536
	global_load_dwordx4 v[22:25], v[152:153], off offset:2560
	v_mad_i64_i32 v[152:153], vcc, s41, v221, v[58:59]
	s_add_u32 s41, s41, 1
	global_load_dwordx4 v[10:13], v[152:153], off offset:1536
	global_load_dwordx4 v[26:29], v[152:153], off offset:2560
	v_mad_i64_i32 v[152:153], vcc, s41, v221, v[58:59]
	s_add_u32 s41, s41, 1
	global_load_dwordx4 v[14:17], v[152:153], off offset:1536
	global_load_dwordx4 v[30:33], v[152:153], off offset:2560
	s_waitcnt vmcnt(6)
	v_lshlrev_b32_e32 v188, 16, v18
	v_and_b32_e32 v189, 0xffff0000, v18
	v_lshlrev_b32_e32 v190, 16, v19
	v_and_b32_e32 v191, 0xffff0000, v19
	v_lshlrev_b32_e32 v192, 16, v20
	v_and_b32_e32 v193, 0xffff0000, v20
	v_lshlrev_b32_e32 v194, 16, v21
	v_and_b32_e32 v195, 0xffff0000, v21
	v_mul_f32_e32 v140, v164, v188
	v_mul_f32_e32 v141, v165, v189
	v_mul_f32_e32 v142, v166, v190
	v_mul_f32_e32 v143, v167, v191
	v_mul_f32_e32 v144, v168, v192
	v_mul_f32_e32 v145, v169, v193
	v_mul_f32_e32 v146, v170, v194
	v_mul_f32_e32 v147, v171, v195
	v_fmac_f32_e32 v140, v172, v204
	v_fmac_f32_e32 v141, v173, v205
	v_fmac_f32_e32 v142, v174, v206
	v_fmac_f32_e32 v143, v175, v207
	v_fmac_f32_e32 v144, v176, v208
	v_fmac_f32_e32 v145, v177, v209
	v_fmac_f32_e32 v146, v178, v210
	v_fmac_f32_e32 v147, v179, v211
	v_fmac_f32_e32 v140, v180, v196
	v_fmac_f32_e32 v141, v181, v197
	v_fmac_f32_e32 v142, v182, v198
	v_fmac_f32_e32 v143, v183, v199
	v_fmac_f32_e32 v144, v184, v200
	v_fmac_f32_e32 v145, v185, v201
	v_fmac_f32_e32 v146, v186, v202
	v_fmac_f32_e32 v147, v187, v203
	v_lshlrev_b32_e32 v150, 16, v2
	v_and_b32_e32 v151, 0xffff0000, v2
	v_mul_f32_e32 v140, v150, v140
	v_mul_f32_e32 v141, v151, v141
	v_lshlrev_b32_e32 v150, 16, v3
	v_and_b32_e32 v151, 0xffff0000, v3
	v_mul_f32_e32 v142, v150, v142
	v_mul_f32_e32 v143, v151, v143
	v_lshlrev_b32_e32 v150, 16, v4
	v_and_b32_e32 v151, 0xffff0000, v4
	v_mul_f32_e32 v144, v150, v144
	v_mul_f32_e32 v145, v151, v145
	v_lshlrev_b32_e32 v150, 16, v5
	v_and_b32_e32 v151, 0xffff0000, v5
	v_mul_f32_e32 v146, v150, v146
	v_mul_f32_e32 v147, v151, v147
	v_mul_f32_e32 v148, v140, v140
	v_fmac_f32_e32 v148, v141, v141
	v_fmac_f32_e32 v148, v142, v142
	v_fmac_f32_e32 v148, v143, v143
	v_fmac_f32_e32 v148, v144, v144
	v_fmac_f32_e32 v148, v145, v145
	v_fmac_f32_e32 v148, v146, v146
	v_fmac_f32_e32 v148, v147, v147
	v_mad_i64_i32 v[152:153], vcc, s41, v221, v[58:59]
	s_add_u32 s41, s41, 1
	global_load_dwordx4 v[2:5], v[152:153], off offset:1536
	global_load_dwordx4 v[18:21], v[152:153], off offset:2560
	s_nop 1
	v_add_f32_dpp v148, v148, v148 quad_perm:[1,0,3,2] row_mask:0xf bank_mask:0xf
	s_nop 1
	v_add_f32_dpp v148, v148, v148 quad_perm:[2,3,0,1] row_mask:0xf bank_mask:0xf
	s_nop 1
	v_add_f32_dpp v148, v148, v148 row_half_mirror row_mask:0xf bank_mask:0xf
	s_nop 1
	v_add_f32_dpp v148, v148, v148 row_mirror row_mask:0xf bank_mask:0xf
	s_nop 1
	v_add_f32_dpp v148, v148, v148 row_bcast:15 row_mask:0xa bank_mask:0xf
	s_nop 1
	v_add_f32_dpp v148, v148, v148 row_bcast:31 row_mask:0xc bank_mask:0xf
	s_nop 0
	v_readlane_b32 s0, v148, 63
	s_nop 0
	v_mov_b32_e32 v148, s0
	v_fmamk_f32 v148, v148, 0x3b000000, v162
	v_mul_f32_e32 v150, 0x4b800000, v148
	v_cmp_gt_f32_e32 vcc, s31, v148
	s_nop 1
	v_cndmask_b32_e32 v148, v148, v150, vcc
	v_rsq_f32_e32 v148, v148
	s_nop 0
	v_mul_f32_e32 v150, 0x45800000, v148
	v_cndmask_b32_e32 v149, v148, v150, vcc
	v_mul_f32_e32 v140, v149, v140
	v_mul_f32_e32 v141, v149, v141
	v_mul_f32_e32 v142, v149, v142
	v_mul_f32_e32 v143, v149, v143
	v_mul_f32_e32 v144, v149, v144
	v_mul_f32_e32 v145, v149, v145
	v_mul_f32_e32 v146, v149, v146
	v_mul_f32_e32 v147, v149, v147
	v_cvt_pk_bf16_f32 v140, v140, v141
	v_cvt_pk_bf16_f32 v141, v142, v143
	v_cvt_pk_bf16_f32 v142, v144, v145
	v_cvt_pk_bf16_f32 v143, v146, v147
	global_store_dwordx4 v[156:157], v[140:143], off
	s_waitcnt vmcnt(7)
	v_lshlrev_b32_e32 v196, 16, v22
	v_and_b32_e32 v197, 0xffff0000, v22
	v_lshlrev_b32_e32 v198, 16, v23
	v_and_b32_e32 v199, 0xffff0000, v23
	v_lshlrev_b32_e32 v200, 16, v24
	v_and_b32_e32 v201, 0xffff0000, v24
	v_lshlrev_b32_e32 v202, 16, v25
	v_and_b32_e32 v203, 0xffff0000, v25
	v_mul_f32_e32 v140, v164, v196
	v_mul_f32_e32 v141, v165, v197
	v_mul_f32_e32 v142, v166, v198
	v_mul_f32_e32 v143, v167, v199
	v_mul_f32_e32 v144, v168, v200
	v_mul_f32_e32 v145, v169, v201
	v_mul_f32_e32 v146, v170, v202
	v_mul_f32_e32 v147, v171, v203
	v_fmac_f32_e32 v140, v172, v188
	v_fmac_f32_e32 v141, v173, v189
	v_fmac_f32_e32 v142, v174, v190
	v_fmac_f32_e32 v143, v175, v191
	v_fmac_f32_e32 v144, v176, v192
	v_fmac_f32_e32 v145, v177, v193
	v_fmac_f32_e32 v146, v178, v194
	v_fmac_f32_e32 v147, v179, v195
	v_fmac_f32_e32 v140, v180, v204
	v_fmac_f32_e32 v141, v181, v205
	v_fmac_f32_e32 v142, v182, v206
	v_fmac_f32_e32 v143, v183, v207
	v_fmac_f32_e32 v144, v184, v208
	v_fmac_f32_e32 v145, v185, v209
	v_fmac_f32_e32 v146, v186, v210
	v_fmac_f32_e32 v147, v187, v211
	v_lshlrev_b32_e32 v150, 16, v6
	v_and_b32_e32 v151, 0xffff0000, v6
	v_mul_f32_e32 v140, v150, v140
	v_mul_f32_e32 v141, v151, v141
	v_lshlrev_b32_e32 v150, 16, v7
	v_and_b32_e32 v151, 0xffff0000, v7
	v_mul_f32_e32 v142, v150, v142
	v_mul_f32_e32 v143, v151, v143
	v_lshlrev_b32_e32 v150, 16, v8
	v_and_b32_e32 v151, 0xffff0000, v8
	v_mul_f32_e32 v144, v150, v144
	v_mul_f32_e32 v145, v151, v145
; __device__ __forceinline__ unsigned cvt_pk_bf16(float lo, float hi) { unsigned r; asm volatile("v_cvt_pk_bf16_f32 %0, %1, %2" : "=v"(r) : "v"(lo), "v"(hi)); return r; }
; __device__ __forceinline__ float bf_lo(unsigned w) { return __uint_as_float(w << 16); }
; __device__ __forceinline__ float bf_hi(unsigned w) { return __uint_as_float(w & 0xffff0000u); }
; __device__ __forceinline__ float wave_sum(float v) {
; #pragma unroll
;     for (int o = 1; o < 64; o <<= 1) v += __shfl_xor(v, o);
;     return v;
; __global__ void __launch_bounds__(512, 2) trunk_fwd(Args args) {
;     ...
;                     float cv[8], uu[8]; float ss = 0.f;
; #pragma unroll
;                     for (int i = 0; i < 4; ++i) {
;                         uu[2 * i] = bf_lo(gu[i]); uu[2 * i + 1] = bf_hi(gu[i]);
;                         cv[2 * i] = bf_lo(gb[i]) * (w0[2 * i] * uu[2 * i] + w1[2 * i] * u1[2 * i] + w2[2 * i] * u2[2 * i]);
;                         cv[2 * i + 1] = bf_hi(gb[i]) * (w0[2 * i + 1] * uu[2 * i + 1] + w1[2 * i + 1] * u1[2 * i + 1] + w2[2 * i + 1] * u2[2 * i + 1]);
;                     }
; #pragma unroll
;                     for (int i = 0; i < 8; ++i) { ss += cv[i] * cv[i]; u2[i] = u1[i]; u1[i] = uu[i]; }
;                     ss = wave_sum(ss);
;                     const float rc = rsqrtf(ss * (1.0f / 512.0f) + EPS);
;                     u32x4 oc;
; #pragma unroll
;                     for (int i = 0; i < 4; ++i) oc[i] = cvt_pk_bf16(cv[2 * i] * rc, cv[2 * i + 1] * rc);
;                     *(u32x4*)(MIX + (size_t)r * 1024 + 512 + c0) = oc;
	v_lshlrev_b32_e32 v150, 16, v9
	v_and_b32_e32 v151, 0xffff0000, v9
	v_mul_f32_e32 v146, v150, v146
	v_mul_f32_e32 v147, v151, v147
	v_mul_f32_e32 v148, v140, v140
	v_fmac_f32_e32 v148, v141, v141
	v_fmac_f32_e32 v148, v142, v142
	v_fmac_f32_e32 v148, v143, v143
	v_fmac_f32_e32 v148, v144, v144
	v_fmac_f32_e32 v148, v145, v145
	v_fmac_f32_e32 v148, v146, v146
	v_fmac_f32_e32 v148, v147, v147
	v_mad_i64_i32 v[152:153], vcc, s41, v221, v[58:59]
	s_add_u32 s41, s41, 1
	global_load_dwordx4 v[6:9], v[152:153], off offset:1536
	global_load_dwordx4 v[22:25], v[152:153], off offset:2560
	s_nop 1
	v_add_f32_dpp v148, v148, v148 quad_perm:[1,0,3,2] row_mask:0xf bank_mask:0xf
	s_nop 1
	v_add_f32_dpp v148, v148, v148 quad_perm:[2,3,0,1] row_mask:0xf bank_mask:0xf
	s_nop 1
	v_add_f32_dpp v148, v148, v148 row_half_mirror row_mask:0xf bank_mask:0xf
	s_nop 1
	v_add_f32_dpp v148, v148, v148 row_mirror row_mask:0xf bank_mask:0xf
	s_nop 1
	v_add_f32_dpp v148, v148, v148 row_bcast:15 row_mask:0xa bank_mask:0xf
	s_nop 1
	v_add_f32_dpp v148, v148, v148 row_bcast:31 row_mask:0xc bank_mask:0xf
	s_nop 0
	v_readlane_b32 s0, v148, 63
	s_nop 0
	v_mov_b32_e32 v148, s0
	v_fmamk_f32 v148, v148, 0x3b000000, v162
	v_mul_f32_e32 v150, 0x4b800000, v148
	v_cmp_gt_f32_e32 vcc, s31, v148
	s_nop 1
	v_cndmask_b32_e32 v148, v148, v150, vcc
	v_rsq_f32_e32 v148, v148
	s_nop 0
	v_mul_f32_e32 v150, 0x45800000, v148
	v_cndmask_b32_e32 v149, v148, v150, vcc
	v_mul_f32_e32 v140, v149, v140
	v_mul_f32_e32 v141, v149, v141
	v_mul_f32_e32 v142, v149, v142
	v_mul_f32_e32 v143, v149, v143
	v_mul_f32_e32 v144, v149, v144
	v_mul_f32_e32 v145, v149, v145
	v_mul_f32_e32 v146, v149, v146
	v_mul_f32_e32 v147, v149, v147
	v_cvt_pk_bf16_f32 v140, v140, v141
	v_cvt_pk_bf16_f32 v141, v142, v143
	v_cvt_pk_bf16_f32 v142, v144, v145
	v_cvt_pk_bf16_f32 v143, v146, v147
	global_store_dwordx4 v[156:157], v[140:143], off offset:2048
	v_lshl_add_u64 v[156:157], v[156:157], 0, s[20:21]
	s_waitcnt vmcnt(8)
	v_lshlrev_b32_e32 v204, 16, v26
	v_and_b32_e32 v205, 0xffff0000, v26
	v_lshlrev_b32_e32 v206, 16, v27
	v_and_b32_e32 v207, 0xffff0000, v27
	v_lshlrev_b32_e32 v208, 16, v28
	v_and_b32_e32 v209, 0xffff0000, v28
	v_lshlrev_b32_e32 v210, 16, v29
	v_and_b32_e32 v211, 0xffff0000, v29
	v_mul_f32_e32 v140, v164, v204
	v_mul_f32_e32 v141, v165, v205
	v_mul_f32_e32 v142, v166, v206
	v_mul_f32_e32 v143, v167, v207
	v_mul_f32_e32 v144, v168, v208
	v_mul_f32_e32 v145, v169, v209
	v_mul_f32_e32 v146, v170, v210
	v_mul_f32_e32 v147, v171, v211
	v_fmac_f32_e32 v140, v172, v196
	v_fmac_f32_e32 v141, v173, v197
	v_fmac_f32_e32 v142, v174, v198
	v_fmac_f32_e32 v143, v175, v199
	v_fmac_f32_e32 v144, v176, v200
	v_fmac_f32_e32 v145, v177, v201
	v_fmac_f32_e32 v146, v178, v202
	v_fmac_f32_e32 v147, v179, v203
	v_fmac_f32_e32 v140, v180, v188
	v_fmac_f32_e32 v141, v181, v189
	v_fmac_f32_e32 v142, v182, v190
	v_fmac_f32_e32 v143, v183, v191
	v_fmac_f32_e32 v144, v184, v192
	v_fmac_f32_e32 v145, v185, v193
	v_fmac_f32_e32 v146, v186, v194
	v_fmac_f32_e32 v147, v187, v195
	v_lshlrev_b32_e32 v150, 16, v10
	v_and_b32_e32 v151, 0xffff0000, v10
	v_mul_f32_e32 v140, v150, v140
	v_mul_f32_e32 v141, v151, v141
	v_lshlrev_b32_e32 v150, 16, v11
	v_and_b32_e32 v151, 0xffff0000, v11
	v_mul_f32_e32 v142, v150, v142
	v_mul_f32_e32 v143, v151, v143
	v_lshlrev_b32_e32 v150, 16, v12
	v_and_b32_e32 v151, 0xffff0000, v12
	v_mul_f32_e32 v144, v150, v144
	v_mul_f32_e32 v145, v151, v145
	v_lshlrev_b32_e32 v150, 16, v13
	v_and_b32_e32 v151, 0xffff0000, v13
	v_mul_f32_e32 v146, v150, v146
	v_mul_f32_e32 v147, v151, v147
	v_mul_f32_e32 v148, v140, v140
	v_fmac_f32_e32 v148, v141, v141
	v_fmac_f32_e32 v148, v142, v142
	v_fmac_f32_e32 v148, v143, v143
	v_fmac_f32_e32 v148, v144, v144
	v_fmac_f32_e32 v148, v145, v145
	v_fmac_f32_e32 v148, v146, v146
	v_fmac_f32_e32 v148, v147, v147
	v_mad_i64_i32 v[152:153], vcc, s41, v221, v[58:59]
	s_add_u32 s41, s41, 1
	global_load_dwordx4 v[10:13], v[152:153], off offset:1536
	global_load_dwordx4 v[26:29], v[152:153], off offset:2560
	s_nop 1
	v_add_f32_dpp v148, v148, v148 quad_perm:[1,0,3,2] row_mask:0xf bank_mask:0xf
	s_nop 1
	v_add_f32_dpp v148, v148, v148 quad_perm:[2,3,0,1] row_mask:0xf bank_mask:0xf
	s_nop 1
	v_add_f32_dpp v148, v148, v148 row_half_mirror row_mask:0xf bank_mask:0xf
	s_nop 1
	v_add_f32_dpp v148, v148, v148 row_mirror row_mask:0xf bank_mask:0xf
	s_nop 1
	v_add_f32_dpp v148, v148, v148 row_bcast:15 row_mask:0xa bank_mask:0xf
	s_nop 1
	v_add_f32_dpp v148, v148, v148 row_bcast:31 row_mask:0xc bank_mask:0xf
	s_nop 0
	v_readlane_b32 s0, v148, 63
	s_nop 0
	v_mov_b32_e32 v148, s0
	v_fmamk_f32 v148, v148, 0x3b000000, v162
	v_mul_f32_e32 v150, 0x4b800000, v148
	v_cmp_gt_f32_e32 vcc, s31, v148
	s_nop 1
	v_cndmask_b32_e32 v148, v148, v150, vcc
	v_rsq_f32_e32 v148, v148
	s_nop 0
	v_mul_f32_e32 v150, 0x45800000, v148
	v_cndmask_b32_e32 v149, v148, v150, vcc
	v_mul_f32_e32 v140, v149, v140
	v_mul_f32_e32 v141, v149, v141
	v_mul_f32_e32 v142, v149, v142
	v_mul_f32_e32 v143, v149, v143
	v_mul_f32_e32 v144, v149, v144
	v_mul_f32_e32 v145, v149, v145
	v_mul_f32_e32 v146, v149, v146
	v_mul_f32_e32 v147, v149, v147
	v_cvt_pk_bf16_f32 v140, v140, v141
	v_cvt_pk_bf16_f32 v141, v142, v143
	v_cvt_pk_bf16_f32 v142, v144, v145
	v_cvt_pk_bf16_f32 v143, v146, v147
	global_store_dwordx4 v[156:157], v[140:143], off
	s_waitcnt vmcnt(9)
; __device__ __forceinline__ unsigned cvt_pk_bf16(float lo, float hi) { unsigned r; asm volatile("v_cvt_pk_bf16_f32 %0, %1, %2" : "=v"(r) : "v"(lo), "v"(hi)); return r; }
; __device__ __forceinline__ float bf_lo(unsigned w) { return __uint_as_float(w << 16); }
; __device__ __forceinline__ float bf_hi(unsigned w) { return __uint_as_float(w & 0xffff0000u); }
; __device__ __forceinline__ float wave_sum(float v) {
; #pragma unroll
;     for (int o = 1; o < 64; o <<= 1) v += __shfl_xor(v, o);
;     return v;
; __global__ void __launch_bounds__(512, 2) trunk_fwd(Args args) {
;     ...
;                     float cv[8], uu[8]; float ss = 0.f;
; #pragma unroll
;                     for (int i = 0; i < 4; ++i) {
;                         uu[2 * i] = bf_lo(gu[i]); uu[2 * i + 1] = bf_hi(gu[i]);
;                         cv[2 * i] = bf_lo(gb[i]) * (w0[2 * i] * uu[2 * i] + w1[2 * i] * u1[2 * i] + w2[2 * i] * u2[2 * i]);
;                         cv[2 * i + 1] = bf_hi(gb[i]) * (w0[2 * i + 1] * uu[2 * i + 1] + w1[2 * i + 1] * u1[2 * i + 1] + w2[2 * i + 1] * u2[2 * i + 1]);
;                     }
; #pragma unroll
;                     for (int i = 0; i < 8; ++i) { ss += cv[i] * cv[i]; u2[i] = u1[i]; u1[i] = uu[i]; }
;                     ss = wave_sum(ss);
;                     const float rc = rsqrtf(ss * (1.0f / 512.0f) + EPS);
;                     u32x4 oc;
; #pragma unroll
;                     for (int i = 0; i < 4; ++i) oc[i] = cvt_pk_bf16(cv[2 * i] * rc, cv[2 * i + 1] * rc);
;                     *(u32x4*)(MIX + (size_t)r * 1024 + 512 + c0) = oc;
	v_lshlrev_b32_e32 v188, 16, v30
	v_and_b32_e32 v189, 0xffff0000, v30
	v_lshlrev_b32_e32 v190, 16, v31
	v_and_b32_e32 v191, 0xffff0000, v31
	v_lshlrev_b32_e32 v192, 16, v32
	v_and_b32_e32 v193, 0xffff0000, v32
	v_lshlrev_b32_e32 v194, 16, v33
	v_and_b32_e32 v195, 0xffff0000, v33
	v_mul_f32_e32 v140, v164, v188
	v_mul_f32_e32 v141, v165, v189
	v_mul_f32_e32 v142, v166, v190
	v_mul_f32_e32 v143, v167, v191
	v_mul_f32_e32 v144, v168, v192
	v_mul_f32_e32 v145, v169, v193
	v_mul_f32_e32 v146, v170, v194
	v_mul_f32_e32 v147, v171, v195
	v_fmac_f32_e32 v140, v172, v204
	v_fmac_f32_e32 v141, v173, v205
	v_fmac_f32_e32 v142, v174, v206
	v_fmac_f32_e32 v143, v175, v207
	v_fmac_f32_e32 v144, v176, v208
	v_fmac_f32_e32 v145, v177, v209
	v_fmac_f32_e32 v146, v178, v210
	v_fmac_f32_e32 v147, v179, v211
	v_fmac_f32_e32 v140, v180, v196
	v_fmac_f32_e32 v141, v181, v197
	v_fmac_f32_e32 v142, v182, v198
	v_fmac_f32_e32 v143, v183, v199
	v_fmac_f32_e32 v144, v184, v200
	v_fmac_f32_e32 v145, v185, v201
	v_fmac_f32_e32 v146, v186, v202
	v_fmac_f32_e32 v147, v187, v203
	v_lshlrev_b32_e32 v150, 16, v14
	v_and_b32_e32 v151, 0xffff0000, v14
	v_mul_f32_e32 v140, v150, v140
	v_mul_f32_e32 v141, v151, v141
	v_lshlrev_b32_e32 v150, 16, v15
	v_and_b32_e32 v151, 0xffff0000, v15
	v_mul_f32_e32 v142, v150, v142
	v_mul_f32_e32 v143, v151, v143
	v_lshlrev_b32_e32 v150, 16, v16
	v_and_b32_e32 v151, 0xffff0000, v16
	v_mul_f32_e32 v144, v150, v144
	v_mul_f32_e32 v145, v151, v145
	v_lshlrev_b32_e32 v150, 16, v17
	v_and_b32_e32 v151, 0xffff0000, v17
	v_mul_f32_e32 v146, v150, v146
	v_mul_f32_e32 v147, v151, v147
	v_mul_f32_e32 v148, v140, v140
	v_fmac_f32_e32 v148, v141, v141
	v_fmac_f32_e32 v148, v142, v142
	v_fmac_f32_e32 v148, v143, v143
	v_fmac_f32_e32 v148, v144, v144
	v_fmac_f32_e32 v148, v145, v145
	v_fmac_f32_e32 v148, v146, v146
	v_fmac_f32_e32 v148, v147, v147
	v_mad_i64_i32 v[152:153], vcc, s41, v221, v[58:59]
	s_add_u32 s41, s41, 1
	global_load_dwordx4 v[14:17], v[152:153], off offset:1536
	global_load_dwordx4 v[30:33], v[152:153], off offset:2560
	s_nop 1
	v_add_f32_dpp v148, v148, v148 quad_perm:[1,0,3,2] row_mask:0xf bank_mask:0xf
	s_nop 1
	v_add_f32_dpp v148, v148, v148 quad_perm:[2,3,0,1] row_mask:0xf bank_mask:0xf
	s_nop 1
	v_add_f32_dpp v148, v148, v148 row_half_mirror row_mask:0xf bank_mask:0xf
	s_nop 1
	v_add_f32_dpp v148, v148, v148 row_mirror row_mask:0xf bank_mask:0xf
	s_nop 1
	v_add_f32_dpp v148, v148, v148 row_bcast:15 row_mask:0xa bank_mask:0xf
	s_nop 1
	v_add_f32_dpp v148, v148, v148 row_bcast:31 row_mask:0xc bank_mask:0xf
	s_nop 0
	v_readlane_b32 s0, v148, 63
	s_nop 0
	v_mov_b32_e32 v148, s0
	v_fmamk_f32 v148, v148, 0x3b000000, v162
	v_mul_f32_e32 v150, 0x4b800000, v148
	v_cmp_gt_f32_e32 vcc, s31, v148
	s_nop 1
	v_cndmask_b32_e32 v148, v148, v150, vcc
	v_rsq_f32_e32 v148, v148
	s_nop 0
	v_mul_f32_e32 v150, 0x45800000, v148
	v_cndmask_b32_e32 v149, v148, v150, vcc
	v_mul_f32_e32 v140, v149, v140
	v_mul_f32_e32 v141, v149, v141
	v_mul_f32_e32 v142, v149, v142
	v_mul_f32_e32 v143, v149, v143
	v_mul_f32_e32 v144, v149, v144
	v_mul_f32_e32 v145, v149, v145
	v_mul_f32_e32 v146, v149, v146
	v_mul_f32_e32 v147, v149, v147
	v_cvt_pk_bf16_f32 v140, v140, v141
	v_cvt_pk_bf16_f32 v141, v142, v143
	v_cvt_pk_bf16_f32 v142, v144, v145
	v_cvt_pk_bf16_f32 v143, v146, v147
	global_store_dwordx4 v[156:157], v[140:143], off offset:2048
	v_lshl_add_u64 v[156:157], v[156:157], 0, s[20:21]
	s_waitcnt vmcnt(10)
	v_lshlrev_b32_e32 v196, 16, v18
	v_and_b32_e32 v197, 0xffff0000, v18
	v_lshlrev_b32_e32 v198, 16, v19
	v_and_b32_e32 v199, 0xffff0000, v19
	v_lshlrev_b32_e32 v200, 16, v20
	v_and_b32_e32 v201, 0xffff0000, v20
	v_lshlrev_b32_e32 v202, 16, v21
	v_and_b32_e32 v203, 0xffff0000, v21
	v_mul_f32_e32 v140, v164, v196
	v_mul_f32_e32 v141, v165, v197
	v_mul_f32_e32 v142, v166, v198
	v_mul_f32_e32 v143, v167, v199
	v_mul_f32_e32 v144, v168, v200
	v_mul_f32_e32 v145, v169, v201
	v_mul_f32_e32 v146, v170, v202
	v_mul_f32_e32 v147, v171, v203
	v_fmac_f32_e32 v140, v172, v188
	v_fmac_f32_e32 v141, v173, v189
	v_fmac_f32_e32 v142, v174, v190
	v_fmac_f32_e32 v143, v175, v191
	v_fmac_f32_e32 v144, v176, v192
	v_fmac_f32_e32 v145, v177, v193
	v_fmac_f32_e32 v146, v178, v194
	v_fmac_f32_e32 v147, v179, v195
	v_fmac_f32_e32 v140, v180, v204
	v_fmac_f32_e32 v141, v181, v205
	v_fmac_f32_e32 v142, v182, v206
	v_fmac_f32_e32 v143, v183, v207
	v_fmac_f32_e32 v144, v184, v208
	v_fmac_f32_e32 v145, v185, v209
	v_fmac_f32_e32 v146, v186, v210
	v_fmac_f32_e32 v147, v187, v211
	v_lshlrev_b32_e32 v150, 16, v2
	v_and_b32_e32 v151, 0xffff0000, v2
	v_mul_f32_e32 v140, v150, v140
	v_mul_f32_e32 v141, v151, v141
	v_lshlrev_b32_e32 v150, 16, v3
	v_and_b32_e32 v151, 0xffff0000, v3
	v_mul_f32_e32 v142, v150, v142
	v_mul_f32_e32 v143, v151, v143
	v_lshlrev_b32_e32 v150, 16, v4
	v_and_b32_e32 v151, 0xffff0000, v4
	v_mul_f32_e32 v144, v150, v144
	v_mul_f32_e32 v145, v151, v145
	v_lshlrev_b32_e32 v150, 16, v5
	v_and_b32_e32 v151, 0xffff0000, v5
	v_mul_f32_e32 v146, v150, v146
	v_mul_f32_e32 v147, v151, v147
	v_mul_f32_e32 v148, v140, v140
	v_fmac_f32_e32 v148, v141, v141
	v_fmac_f32_e32 v148, v142, v142
	v_fmac_f32_e32 v148, v143, v143
	v_fmac_f32_e32 v148, v144, v144
	v_fmac_f32_e32 v148, v145, v145
	v_fmac_f32_e32 v148, v146, v146
	v_fmac_f32_e32 v148, v147, v147
	v_mad_i64_i32 v[152:153], vcc, s41, v221, v[58:59]
	s_add_u32 s41, s41, 1
	global_load_dwordx4 v[2:5], v[152:153], off offset:1536
	global_load_dwordx4 v[18:21], v[152:153], off offset:2560
	s_nop 1
	v_add_f32_dpp v148, v148, v148 quad_perm:[1,0,3,2] row_mask:0xf bank_mask:0xf
	s_nop 1
	v_add_f32_dpp v148, v148, v148 quad_perm:[2,3,0,1] row_mask:0xf bank_mask:0xf
	s_nop 1
	v_add_f32_dpp v148, v148, v148 row_half_mirror row_mask:0xf bank_mask:0xf
	s_nop 1
	v_add_f32_dpp v148, v148, v148 row_mirror row_mask:0xf bank_mask:0xf
	s_nop 1
	v_add_f32_dpp v148, v148, v148 row_bcast:15 row_mask:0xa bank_mask:0xf
	s_nop 1
	v_add_f32_dpp v148, v148, v148 row_bcast:31 row_mask:0xc bank_mask:0xf
	s_nop 0
	v_readlane_b32 s0, v148, 63
	s_nop 0
	v_mov_b32_e32 v148, s0
	v_fmamk_f32 v148, v148, 0x3b000000, v162
	v_mul_f32_e32 v150, 0x4b800000, v148
	v_cmp_gt_f32_e32 vcc, s31, v148
	s_nop 1
	v_cndmask_b32_e32 v148, v148, v150, vcc
	v_rsq_f32_e32 v148, v148
	s_nop 0
	v_mul_f32_e32 v150, 0x45800000, v148
	v_cndmask_b32_e32 v149, v148, v150, vcc
	v_mul_f32_e32 v140, v149, v140
	v_mul_f32_e32 v141, v149, v141
	v_mul_f32_e32 v142, v149, v142
	v_mul_f32_e32 v143, v149, v143
	v_mul_f32_e32 v144, v149, v144
	v_mul_f32_e32 v145, v149, v145
	v_mul_f32_e32 v146, v149, v146
	v_mul_f32_e32 v147, v149, v147
	v_cvt_pk_bf16_f32 v140, v140, v141
	v_cvt_pk_bf16_f32 v141, v142, v143
	v_cvt_pk_bf16_f32 v142, v144, v145
	v_cvt_pk_bf16_f32 v143, v146, v147
	global_store_dwordx4 v[156:157], v[140:143], off
	s_waitcnt vmcnt(10)
; __device__ __forceinline__ unsigned cvt_pk_bf16(float lo, float hi) { unsigned r; asm volatile("v_cvt_pk_bf16_f32 %0, %1, %2" : "=v"(r) : "v"(lo), "v"(hi)); return r; }
; __device__ __forceinline__ float bf_lo(unsigned w) { return __uint_as_float(w << 16); }
; __device__ __forceinline__ float bf_hi(unsigned w) { return __uint_as_float(w & 0xffff0000u); }
; __device__ __forceinline__ float wave_sum(float v) {
; #pragma unroll
;     for (int o = 1; o < 64; o <<= 1) v += __shfl_xor(v, o);
;     return v;
; __global__ void __launch_bounds__(512, 2) trunk_fwd(Args args) {
;     ...
;                     float cv[8], uu[8]; float ss = 0.f;
; #pragma unroll
;                     for (int i = 0; i < 4; ++i) {
;                         uu[2 * i] = bf_lo(gu[i]); uu[2 * i + 1] = bf_hi(gu[i]);
;                         cv[2 * i] = bf_lo(gb[i]) * (w0[2 * i] * uu[2 * i] + w1[2 * i] * u1[2 * i] + w2[2 * i] * u2[2 * i]);
;                         cv[2 * i + 1] = bf_hi(gb[i]) * (w0[2 * i + 1] * uu[2 * i + 1] + w1[2 * i + 1] * u1[2 * i + 1] + w2[2 * i + 1] * u2[2 * i + 1]);
;                     }
; #pragma unroll
;                     for (int i = 0; i < 8; ++i) { ss += cv[i] * cv[i]; u2[i] = u1[i]; u1[i] = uu[i]; }
;                     ss = wave_sum(ss);
;                     const float rc = rsqrtf(ss * (1.0f / 512.0f) + EPS);
;                     u32x4 oc;
; #pragma unroll
;                     for (int i = 0; i < 4; ++i) oc[i] = cvt_pk_bf16(cv[2 * i] * rc, cv[2 * i + 1] * rc);
;                     *(u32x4*)(MIX + (size_t)r * 1024 + 512 + c0) = oc;
	v_lshlrev_b32_e32 v204, 16, v22
	v_and_b32_e32 v205, 0xffff0000, v22
	v_lshlrev_b32_e32 v206, 16, v23
	v_and_b32_e32 v207, 0xffff0000, v23
	v_lshlrev_b32_e32 v208, 16, v24
	v_and_b32_e32 v209, 0xffff0000, v24
	v_lshlrev_b32_e32 v210, 16, v25
	v_and_b32_e32 v211, 0xffff0000, v25
	v_mul_f32_e32 v140, v164, v204
	v_mul_f32_e32 v141, v165, v205
	v_mul_f32_e32 v142, v166, v206
	v_mul_f32_e32 v143, v167, v207
	v_mul_f32_e32 v144, v168, v208
	v_mul_f32_e32 v145, v169, v209
	v_mul_f32_e32 v146, v170, v210
	v_mul_f32_e32 v147, v171, v211
	v_fmac_f32_e32 v140, v172, v196
	v_fmac_f32_e32 v141, v173, v197
	v_fmac_f32_e32 v142, v174, v198
	v_fmac_f32_e32 v143, v175, v199
	v_fmac_f32_e32 v144, v176, v200
	v_fmac_f32_e32 v145, v177, v201
	v_fmac_f32_e32 v146, v178, v202
	v_fmac_f32_e32 v147, v179, v203
	v_fmac_f32_e32 v140, v180, v188
	v_fmac_f32_e32 v141, v181, v189
	v_fmac_f32_e32 v142, v182, v190
	v_fmac_f32_e32 v143, v183, v191
	v_fmac_f32_e32 v144, v184, v192
	v_fmac_f32_e32 v145, v185, v193
	v_fmac_f32_e32 v146, v186, v194
	v_fmac_f32_e32 v147, v187, v195
	v_lshlrev_b32_e32 v150, 16, v6
	v_and_b32_e32 v151, 0xffff0000, v6
	v_mul_f32_e32 v140, v150, v140
	v_mul_f32_e32 v141, v151, v141
	v_lshlrev_b32_e32 v150, 16, v7
	v_and_b32_e32 v151, 0xffff0000, v7
	v_mul_f32_e32 v142, v150, v142
	v_mul_f32_e32 v143, v151, v143
	v_lshlrev_b32_e32 v150, 16, v8
	v_and_b32_e32 v151, 0xffff0000, v8
	v_mul_f32_e32 v144, v150, v144
	v_mul_f32_e32 v145, v151, v145
	v_lshlrev_b32_e32 v150, 16, v9
	v_and_b32_e32 v151, 0xffff0000, v9
	v_mul_f32_e32 v146, v150, v146
	v_mul_f32_e32 v147, v151, v147
	v_mul_f32_e32 v148, v140, v140
	v_fmac_f32_e32 v148, v141, v141
	v_fmac_f32_e32 v148, v142, v142
	v_fmac_f32_e32 v148, v143, v143
	v_fmac_f32_e32 v148, v144, v144
	v_fmac_f32_e32 v148, v145, v145
	v_fmac_f32_e32 v148, v146, v146
	v_fmac_f32_e32 v148, v147, v147
	v_mad_i64_i32 v[152:153], vcc, s41, v221, v[58:59]
	s_add_u32 s41, s41, 1
	global_load_dwordx4 v[6:9], v[152:153], off offset:1536
	global_load_dwordx4 v[22:25], v[152:153], off offset:2560
	s_nop 1
	v_add_f32_dpp v148, v148, v148 quad_perm:[1,0,3,2] row_mask:0xf bank_mask:0xf
	s_nop 1
	v_add_f32_dpp v148, v148, v148 quad_perm:[2,3,0,1] row_mask:0xf bank_mask:0xf
	s_nop 1
	v_add_f32_dpp v148, v148, v148 row_half_mirror row_mask:0xf bank_mask:0xf
	s_nop 1
	v_add_f32_dpp v148, v148, v148 row_mirror row_mask:0xf bank_mask:0xf
	s_nop 1
	v_add_f32_dpp v148, v148, v148 row_bcast:15 row_mask:0xa bank_mask:0xf
	s_nop 1
	v_add_f32_dpp v148, v148, v148 row_bcast:31 row_mask:0xc bank_mask:0xf
	s_nop 0
	v_readlane_b32 s0, v148, 63
	s_nop 0
	v_mov_b32_e32 v148, s0
	v_fmamk_f32 v148, v148, 0x3b000000, v162
	v_mul_f32_e32 v150, 0x4b800000, v148
	v_cmp_gt_f32_e32 vcc, s31, v148
	s_nop 1
	v_cndmask_b32_e32 v148, v148, v150, vcc
	v_rsq_f32_e32 v148, v148
	s_nop 0
	v_mul_f32_e32 v150, 0x45800000, v148
	v_cndmask_b32_e32 v149, v148, v150, vcc
	v_mul_f32_e32 v140, v149, v140
	v_mul_f32_e32 v141, v149, v141
	v_mul_f32_e32 v142, v149, v142
	v_mul_f32_e32 v143, v149, v143
	v_mul_f32_e32 v144, v149, v144
	v_mul_f32_e32 v145, v149, v145
	v_mul_f32_e32 v146, v149, v146
	v_mul_f32_e32 v147, v149, v147
	v_cvt_pk_bf16_f32 v140, v140, v141
	v_cvt_pk_bf16_f32 v141, v142, v143
	v_cvt_pk_bf16_f32 v142, v144, v145
	v_cvt_pk_bf16_f32 v143, v146, v147
	global_store_dwordx4 v[156:157], v[140:143], off offset:2048
	v_lshl_add_u64 v[156:157], v[156:157], 0, s[20:21]
	s_waitcnt vmcnt(10)
	v_lshlrev_b32_e32 v188, 16, v26
	v_and_b32_e32 v189, 0xffff0000, v26
	v_lshlrev_b32_e32 v190, 16, v27
	v_and_b32_e32 v191, 0xffff0000, v27
	v_lshlrev_b32_e32 v192, 16, v28
	v_and_b32_e32 v193, 0xffff0000, v28
	v_lshlrev_b32_e32 v194, 16, v29
	v_and_b32_e32 v195, 0xffff0000, v29
	v_mul_f32_e32 v140, v164, v188
	v_mul_f32_e32 v141, v165, v189
	v_mul_f32_e32 v142, v166, v190
	v_mul_f32_e32 v143, v167, v191
	v_mul_f32_e32 v144, v168, v192
	v_mul_f32_e32 v145, v169, v193
	v_mul_f32_e32 v146, v170, v194
	v_mul_f32_e32 v147, v171, v195
	v_fmac_f32_e32 v140, v172, v204
	v_fmac_f32_e32 v141, v173, v205
	v_fmac_f32_e32 v142, v174, v206
	v_fmac_f32_e32 v143, v175, v207
	v_fmac_f32_e32 v144, v176, v208
	v_fmac_f32_e32 v145, v177, v209
	v_fmac_f32_e32 v146, v178, v210
	v_fmac_f32_e32 v147, v179, v211
	v_fmac_f32_e32 v140, v180, v196
	v_fmac_f32_e32 v141, v181, v197
	v_fmac_f32_e32 v142, v182, v198
	v_fmac_f32_e32 v143, v183, v199
	v_fmac_f32_e32 v144, v184, v200
	v_fmac_f32_e32 v145, v185, v201
	v_fmac_f32_e32 v146, v186, v202
	v_fmac_f32_e32 v147, v187, v203
	v_lshlrev_b32_e32 v150, 16, v10
	v_and_b32_e32 v151, 0xffff0000, v10
	v_mul_f32_e32 v140, v150, v140
	v_mul_f32_e32 v141, v151, v141
	v_lshlrev_b32_e32 v150, 16, v11
	v_and_b32_e32 v151, 0xffff0000, v11
	v_mul_f32_e32 v142, v150, v142
	v_mul_f32_e32 v143, v151, v143
	v_lshlrev_b32_e32 v150, 16, v12
	v_and_b32_e32 v151, 0xffff0000, v12
	v_mul_f32_e32 v144, v150, v144
	v_mul_f32_e32 v145, v151, v145
	v_lshlrev_b32_e32 v150, 16, v13
	v_and_b32_e32 v151, 0xffff0000, v13
	v_mul_f32_e32 v146, v150, v146
	v_mul_f32_e32 v147, v151, v147
	v_mul_f32_e32 v148, v140, v140
	v_fmac_f32_e32 v148, v141, v141
	v_fmac_f32_e32 v148, v142, v142
	v_fmac_f32_e32 v148, v143, v143
	v_fmac_f32_e32 v148, v144, v144
	v_fmac_f32_e32 v148, v145, v145
	v_fmac_f32_e32 v148, v146, v146
	v_fmac_f32_e32 v148, v147, v147
	v_mad_i64_i32 v[152:153], vcc, s41, v221, v[58:59]
	s_add_u32 s41, s41, 1
	global_load_dwordx4 v[10:13], v[152:153], off offset:1536
	global_load_dwordx4 v[26:29], v[152:153], off offset:2560
	s_nop 1
	v_add_f32_dpp v148, v148, v148 quad_perm:[1,0,3,2] row_mask:0xf bank_mask:0xf
	s_nop 1
	v_add_f32_dpp v148, v148, v148 quad_perm:[2,3,0,1] row_mask:0xf bank_mask:0xf
	s_nop 1
	v_add_f32_dpp v148, v148, v148 row_half_mirror row_mask:0xf bank_mask:0xf
	s_nop 1
	v_add_f32_dpp v148, v148, v148 row_mirror row_mask:0xf bank_mask:0xf
	s_nop 1
	v_add_f32_dpp v148, v148, v148 row_bcast:15 row_mask:0xa bank_mask:0xf
	s_nop 1
	v_add_f32_dpp v148, v148, v148 row_bcast:31 row_mask:0xc bank_mask:0xf
	s_nop 0
	v_readlane_b32 s0, v148, 63
	s_nop 0
	v_mov_b32_e32 v148, s0
	v_fmamk_f32 v148, v148, 0x3b000000, v162
	v_mul_f32_e32 v150, 0x4b800000, v148
	v_cmp_gt_f32_e32 vcc, s31, v148
	s_nop 1
	v_cndmask_b32_e32 v148, v148, v150, vcc
	v_rsq_f32_e32 v148, v148
	s_nop 0
	v_mul_f32_e32 v150, 0x45800000, v148
	v_cndmask_b32_e32 v149, v148, v150, vcc
	v_mul_f32_e32 v140, v149, v140
	v_mul_f32_e32 v141, v149, v141
	v_mul_f32_e32 v142, v149, v142
	v_mul_f32_e32 v143, v149, v143
	v_mul_f32_e32 v144, v149, v144
	v_mul_f32_e32 v145, v149, v145
	v_mul_f32_e32 v146, v149, v146
	v_mul_f32_e32 v147, v149, v147
	v_cvt_pk_bf16_f32 v140, v140, v141
	v_cvt_pk_bf16_f32 v141, v142, v143
	v_cvt_pk_bf16_f32 v142, v144, v145
	v_cvt_pk_bf16_f32 v143, v146, v147
	global_store_dwordx4 v[156:157], v[140:143], off
	s_waitcnt vmcnt(10)
; __device__ __forceinline__ unsigned cvt_pk_bf16(float lo, float hi) { unsigned r; asm volatile("v_cvt_pk_bf16_f32 %0, %1, %2" : "=v"(r) : "v"(lo), "v"(hi)); return r; }
; __device__ __forceinline__ float bf_lo(unsigned w) { return __uint_as_float(w << 16); }
; __device__ __forceinline__ float bf_hi(unsigned w) { return __uint_as_float(w & 0xffff0000u); }
; __device__ __forceinline__ float wave_sum(float v) {
; #pragma unroll
;     for (int o = 1; o < 64; o <<= 1) v += __shfl_xor(v, o);
;     return v;
; __global__ void __launch_bounds__(512, 2) trunk_fwd(Args args) {
;     ...
;                     float cv[8], uu[8]; float ss = 0.f;
; #pragma unroll
;                     for (int i = 0; i < 4; ++i) {
;                         uu[2 * i] = bf_lo(gu[i]); uu[2 * i + 1] = bf_hi(gu[i]);
;                         cv[2 * i] = bf_lo(gb[i]) * (w0[2 * i] * uu[2 * i] + w1[2 * i] * u1[2 * i] + w2[2 * i] * u2[2 * i]);
;                         cv[2 * i + 1] = bf_hi(gb[i]) * (w0[2 * i + 1] * uu[2 * i + 1] + w1[2 * i + 1] * u1[2 * i + 1] + w2[2 * i + 1] * u2[2 * i + 1]);
;                     }
; #pragma unroll
;                     for (int i = 0; i < 8; ++i) { ss += cv[i] * cv[i]; u2[i] = u1[i]; u1[i] = uu[i]; }
;                     ss = wave_sum(ss);
;                     const float rc = rsqrtf(ss * (1.0f / 512.0f) + EPS);
;                     u32x4 oc;
; #pragma unroll
;                     for (int i = 0; i < 4; ++i) oc[i] = cvt_pk_bf16(cv[2 * i] * rc, cv[2 * i + 1] * rc);
;                     *(u32x4*)(MIX + (size_t)r * 1024 + 512 + c0) = oc;
	v_lshlrev_b32_e32 v196, 16, v30
	v_and_b32_e32 v197, 0xffff0000, v30
	v_lshlrev_b32_e32 v198, 16, v31
	v_and_b32_e32 v199, 0xffff0000, v31
	v_lshlrev_b32_e32 v200, 16, v32
	v_and_b32_e32 v201, 0xffff0000, v32
	v_lshlrev_b32_e32 v202, 16, v33
	v_and_b32_e32 v203, 0xffff0000, v33
	v_mul_f32_e32 v140, v164, v196
	v_mul_f32_e32 v141, v165, v197
	v_mul_f32_e32 v142, v166, v198
	v_mul_f32_e32 v143, v167, v199
	v_mul_f32_e32 v144, v168, v200
	v_mul_f32_e32 v145, v169, v201
	v_mul_f32_e32 v146, v170, v202
	v_mul_f32_e32 v147, v171, v203
	v_fmac_f32_e32 v140, v172, v188
	v_fmac_f32_e32 v141, v173, v189
	v_fmac_f32_e32 v142, v174, v190
	v_fmac_f32_e32 v143, v175, v191
	v_fmac_f32_e32 v144, v176, v192
	v_fmac_f32_e32 v145, v177, v193
	v_fmac_f32_e32 v146, v178, v194
	v_fmac_f32_e32 v147, v179, v195
	v_fmac_f32_e32 v140, v180, v204
	v_fmac_f32_e32 v141, v181, v205
	v_fmac_f32_e32 v142, v182, v206
	v_fmac_f32_e32 v143, v183, v207
	v_fmac_f32_e32 v144, v184, v208
	v_fmac_f32_e32 v145, v185, v209
	v_fmac_f32_e32 v146, v186, v210
	v_fmac_f32_e32 v147, v187, v211
	v_lshlrev_b32_e32 v150, 16, v14
	v_and_b32_e32 v151, 0xffff0000, v14
	v_mul_f32_e32 v140, v150, v140
	v_mul_f32_e32 v141, v151, v141
	v_lshlrev_b32_e32 v150, 16, v15
	v_and_b32_e32 v151, 0xffff0000, v15
	v_mul_f32_e32 v142, v150, v142
	v_mul_f32_e32 v143, v151, v143
	v_lshlrev_b32_e32 v150, 16, v16
	v_and_b32_e32 v151, 0xffff0000, v16
	v_mul_f32_e32 v144, v150, v144
	v_mul_f32_e32 v145, v151, v145
	v_lshlrev_b32_e32 v150, 16, v17
	v_and_b32_e32 v151, 0xffff0000, v17
	v_mul_f32_e32 v146, v150, v146
	v_mul_f32_e32 v147, v151, v147
	v_mul_f32_e32 v148, v140, v140
	v_fmac_f32_e32 v148, v141, v141
	v_fmac_f32_e32 v148, v142, v142
	v_fmac_f32_e32 v148, v143, v143
	v_fmac_f32_e32 v148, v144, v144
	v_fmac_f32_e32 v148, v145, v145
	v_fmac_f32_e32 v148, v146, v146
	v_fmac_f32_e32 v148, v147, v147
	v_mad_i64_i32 v[152:153], vcc, s41, v221, v[58:59]
	s_add_u32 s41, s41, 1
	global_load_dwordx4 v[14:17], v[152:153], off offset:1536
	global_load_dwordx4 v[30:33], v[152:153], off offset:2560
	s_nop 1
	v_add_f32_dpp v148, v148, v148 quad_perm:[1,0,3,2] row_mask:0xf bank_mask:0xf
	s_nop 1
	v_add_f32_dpp v148, v148, v148 quad_perm:[2,3,0,1] row_mask:0xf bank_mask:0xf
	s_nop 1
	v_add_f32_dpp v148, v148, v148 row_half_mirror row_mask:0xf bank_mask:0xf
	s_nop 1
	v_add_f32_dpp v148, v148, v148 row_mirror row_mask:0xf bank_mask:0xf
	s_nop 1
	v_add_f32_dpp v148, v148, v148 row_bcast:15 row_mask:0xa bank_mask:0xf
	s_nop 1
	v_add_f32_dpp v148, v148, v148 row_bcast:31 row_mask:0xc bank_mask:0xf
	s_nop 0
	v_readlane_b32 s0, v148, 63
	s_nop 0
	v_mov_b32_e32 v148, s0
	v_fmamk_f32 v148, v148, 0x3b000000, v162
	v_mul_f32_e32 v150, 0x4b800000, v148
	v_cmp_gt_f32_e32 vcc, s31, v148
	s_nop 1
	v_cndmask_b32_e32 v148, v148, v150, vcc
	v_rsq_f32_e32 v148, v148
	s_nop 0
	v_mul_f32_e32 v150, 0x45800000, v148
	v_cndmask_b32_e32 v149, v148, v150, vcc
	v_mul_f32_e32 v140, v149, v140
	v_mul_f32_e32 v141, v149, v141
	v_mul_f32_e32 v142, v149, v142
	v_mul_f32_e32 v143, v149, v143
	v_mul_f32_e32 v144, v149, v144
	v_mul_f32_e32 v145, v149, v145
	v_mul_f32_e32 v146, v149, v146
	v_mul_f32_e32 v147, v149, v147
	v_cvt_pk_bf16_f32 v140, v140, v141
	v_cvt_pk_bf16_f32 v141, v142, v143
	v_cvt_pk_bf16_f32 v142, v144, v145
	v_cvt_pk_bf16_f32 v143, v146, v147
	global_store_dwordx4 v[156:157], v[140:143], off offset:2048
	v_lshl_add_u64 v[156:157], v[156:157], 0, s[20:21]
	s_waitcnt vmcnt(10)
	v_lshlrev_b32_e32 v204, 16, v18
	v_and_b32_e32 v205, 0xffff0000, v18
	v_lshlrev_b32_e32 v206, 16, v19
	v_and_b32_e32 v207, 0xffff0000, v19
	v_lshlrev_b32_e32 v208, 16, v20
	v_and_b32_e32 v209, 0xffff0000, v20
	v_lshlrev_b32_e32 v210, 16, v21
	v_and_b32_e32 v211, 0xffff0000, v21
	v_mul_f32_e32 v140, v164, v204
	v_mul_f32_e32 v141, v165, v205
	v_mul_f32_e32 v142, v166, v206
	v_mul_f32_e32 v143, v167, v207
	v_mul_f32_e32 v144, v168, v208
	v_mul_f32_e32 v145, v169, v209
	v_mul_f32_e32 v146, v170, v210
	v_mul_f32_e32 v147, v171, v211
	v_fmac_f32_e32 v140, v172, v196
	v_fmac_f32_e32 v141, v173, v197
	v_fmac_f32_e32 v142, v174, v198
	v_fmac_f32_e32 v143, v175, v199
	v_fmac_f32_e32 v144, v176, v200
	v_fmac_f32_e32 v145, v177, v201
	v_fmac_f32_e32 v146, v178, v202
	v_fmac_f32_e32 v147, v179, v203
	v_fmac_f32_e32 v140, v180, v188
	v_fmac_f32_e32 v141, v181, v189
	v_fmac_f32_e32 v142, v182, v190
	v_fmac_f32_e32 v143, v183, v191
	v_fmac_f32_e32 v144, v184, v192
	v_fmac_f32_e32 v145, v185, v193
	v_fmac_f32_e32 v146, v186, v194
	v_fmac_f32_e32 v147, v187, v195
	v_lshlrev_b32_e32 v150, 16, v2
	v_and_b32_e32 v151, 0xffff0000, v2
	v_mul_f32_e32 v140, v150, v140
	v_mul_f32_e32 v141, v151, v141
	v_lshlrev_b32_e32 v150, 16, v3
	v_and_b32_e32 v151, 0xffff0000, v3
	v_mul_f32_e32 v142, v150, v142
	v_mul_f32_e32 v143, v151, v143
	v_lshlrev_b32_e32 v150, 16, v4
	v_and_b32_e32 v151, 0xffff0000, v4
	v_mul_f32_e32 v144, v150, v144
	v_mul_f32_e32 v145, v151, v145
	v_lshlrev_b32_e32 v150, 16, v5
	v_and_b32_e32 v151, 0xffff0000, v5
	v_mul_f32_e32 v146, v150, v146
	v_mul_f32_e32 v147, v151, v147
	v_mul_f32_e32 v148, v140, v140
	v_fmac_f32_e32 v148, v141, v141
	v_fmac_f32_e32 v148, v142, v142
	v_fmac_f32_e32 v148, v143, v143
	v_fmac_f32_e32 v148, v144, v144
	v_fmac_f32_e32 v148, v145, v145
	v_fmac_f32_e32 v148, v146, v146
	v_fmac_f32_e32 v148, v147, v147
	v_mad_i64_i32 v[152:153], vcc, s41, v221, v[58:59]
	s_add_u32 s41, s41, 1
	global_load_dwordx4 v[2:5], v[152:153], off offset:1536
	global_load_dwordx4 v[18:21], v[152:153], off offset:2560
	s_nop 1
	v_add_f32_dpp v148, v148, v148 quad_perm:[1,0,3,2] row_mask:0xf bank_mask:0xf
	s_nop 1
	v_add_f32_dpp v148, v148, v148 quad_perm:[2,3,0,1] row_mask:0xf bank_mask:0xf
	s_nop 1
	v_add_f32_dpp v148, v148, v148 row_half_mirror row_mask:0xf bank_mask:0xf
	s_nop 1
	v_add_f32_dpp v148, v148, v148 row_mirror row_mask:0xf bank_mask:0xf
	s_nop 1
	v_add_f32_dpp v148, v148, v148 row_bcast:15 row_mask:0xa bank_mask:0xf
	s_nop 1
	v_add_f32_dpp v148, v148, v148 row_bcast:31 row_mask:0xc bank_mask:0xf
	s_nop 0
	v_readlane_b32 s0, v148, 63
	s_nop 0
	v_mov_b32_e32 v148, s0
	v_fmamk_f32 v148, v148, 0x3b000000, v162
	v_mul_f32_e32 v150, 0x4b800000, v148
	v_cmp_gt_f32_e32 vcc, s31, v148
	s_nop 1
	v_cndmask_b32_e32 v148, v148, v150, vcc
	v_rsq_f32_e32 v148, v148
	s_nop 0
	v_mul_f32_e32 v150, 0x45800000, v148
	v_cndmask_b32_e32 v149, v148, v150, vcc
	v_mul_f32_e32 v140, v149, v140
	v_mul_f32_e32 v141, v149, v141
	v_mul_f32_e32 v142, v149, v142
	v_mul_f32_e32 v143, v149, v143
	v_mul_f32_e32 v144, v149, v144
	v_mul_f32_e32 v145, v149, v145
	v_mul_f32_e32 v146, v149, v146
	v_mul_f32_e32 v147, v149, v147
	v_cvt_pk_bf16_f32 v140, v140, v141
	v_cvt_pk_bf16_f32 v141, v142, v143
	v_cvt_pk_bf16_f32 v142, v144, v145
	v_cvt_pk_bf16_f32 v143, v146, v147
	global_store_dwordx4 v[156:157], v[140:143], off
	s_waitcnt vmcnt(10)
; __device__ __forceinline__ unsigned cvt_pk_bf16(float lo, float hi) { unsigned r; asm volatile("v_cvt_pk_bf16_f32 %0, %1, %2" : "=v"(r) : "v"(lo), "v"(hi)); return r; }
; __device__ __forceinline__ float bf_lo(unsigned w) { return __uint_as_float(w << 16); }
; __device__ __forceinline__ float bf_hi(unsigned w) { return __uint_as_float(w & 0xffff0000u); }
; __device__ __forceinline__ float wave_sum(float v) {
; #pragma unroll
;     for (int o = 1; o < 64; o <<= 1) v += __shfl_xor(v, o);
;     return v;
; __global__ void __launch_bounds__(512, 2) trunk_fwd(Args args) {
;     ...
;                     float cv[8], uu[8]; float ss = 0.f;
; #pragma unroll
;                     for (int i = 0; i < 4; ++i) {
;                         uu[2 * i] = bf_lo(gu[i]); uu[2 * i + 1] = bf_hi(gu[i]);
;                         cv[2 * i] = bf_lo(gb[i]) * (w0[2 * i] * uu[2 * i] + w1[2 * i] * u1[2 * i] + w2[2 * i] * u2[2 * i]);
;                         cv[2 * i + 1] = bf_hi(gb[i]) * (w0[2 * i + 1] * uu[2 * i + 1] + w1[2 * i + 1] * u1[2 * i + 1] + w2[2 * i + 1] * u2[2 * i + 1]);
;                     }
; #pragma unroll
;                     for (int i = 0; i < 8; ++i) { ss += cv[i] * cv[i]; u2[i] = u1[i]; u1[i] = uu[i]; }
;                     ss = wave_sum(ss);
;                     const float rc = rsqrtf(ss * (1.0f / 512.0f) + EPS);
;                     u32x4 oc;
; #pragma unroll
;                     for (int i = 0; i < 4; ++i) oc[i] = cvt_pk_bf16(cv[2 * i] * rc, cv[2 * i + 1] * rc);
;                     *(u32x4*)(MIX + (size_t)r * 1024 + 512 + c0) = oc;
	v_lshlrev_b32_e32 v188, 16, v22
	v_and_b32_e32 v189, 0xffff0000, v22
	v_lshlrev_b32_e32 v190, 16, v23
	v_and_b32_e32 v191, 0xffff0000, v23
	v_lshlrev_b32_e32 v192, 16, v24
	v_and_b32_e32 v193, 0xffff0000, v24
	v_lshlrev_b32_e32 v194, 16, v25
	v_and_b32_e32 v195, 0xffff0000, v25
	v_mul_f32_e32 v140, v164, v188
	v_mul_f32_e32 v141, v165, v189
	v_mul_f32_e32 v142, v166, v190
	v_mul_f32_e32 v143, v167, v191
	v_mul_f32_e32 v144, v168, v192
	v_mul_f32_e32 v145, v169, v193
	v_mul_f32_e32 v146, v170, v194
	v_mul_f32_e32 v147, v171, v195
	v_fmac_f32_e32 v140, v172, v204
	v_fmac_f32_e32 v141, v173, v205
	v_fmac_f32_e32 v142, v174, v206
	v_fmac_f32_e32 v143, v175, v207
	v_fmac_f32_e32 v144, v176, v208
	v_fmac_f32_e32 v145, v177, v209
	v_fmac_f32_e32 v146, v178, v210
	v_fmac_f32_e32 v147, v179, v211
	v_fmac_f32_e32 v140, v180, v196
	v_fmac_f32_e32 v141, v181, v197
	v_fmac_f32_e32 v142, v182, v198
	v_fmac_f32_e32 v143, v183, v199
	v_fmac_f32_e32 v144, v184, v200
	v_fmac_f32_e32 v145, v185, v201
	v_fmac_f32_e32 v146, v186, v202
	v_fmac_f32_e32 v147, v187, v203
	v_lshlrev_b32_e32 v150, 16, v6
	v_and_b32_e32 v151, 0xffff0000, v6
	v_mul_f32_e32 v140, v150, v140
	v_mul_f32_e32 v141, v151, v141
	v_lshlrev_b32_e32 v150, 16, v7
	v_and_b32_e32 v151, 0xffff0000, v7
	v_mul_f32_e32 v142, v150, v142
	v_mul_f32_e32 v143, v151, v143
	v_lshlrev_b32_e32 v150, 16, v8
	v_and_b32_e32 v151, 0xffff0000, v8
	v_mul_f32_e32 v144, v150, v144
	v_mul_f32_e32 v145, v151, v145
	v_lshlrev_b32_e32 v150, 16, v9
	v_and_b32_e32 v151, 0xffff0000, v9
	v_mul_f32_e32 v146, v150, v146
	v_mul_f32_e32 v147, v151, v147
	v_mul_f32_e32 v148, v140, v140
	v_fmac_f32_e32 v148, v141, v141
	v_fmac_f32_e32 v148, v142, v142
	v_fmac_f32_e32 v148, v143, v143
	v_fmac_f32_e32 v148, v144, v144
	v_fmac_f32_e32 v148, v145, v145
	v_fmac_f32_e32 v148, v146, v146
	v_fmac_f32_e32 v148, v147, v147
	v_mad_i64_i32 v[152:153], vcc, s41, v221, v[58:59]
	s_add_u32 s41, s41, 1
	global_load_dwordx4 v[6:9], v[152:153], off offset:1536
	global_load_dwordx4 v[22:25], v[152:153], off offset:2560
	s_nop 1
	v_add_f32_dpp v148, v148, v148 quad_perm:[1,0,3,2] row_mask:0xf bank_mask:0xf
	s_nop 1
	v_add_f32_dpp v148, v148, v148 quad_perm:[2,3,0,1] row_mask:0xf bank_mask:0xf
	s_nop 1
	v_add_f32_dpp v148, v148, v148 row_half_mirror row_mask:0xf bank_mask:0xf
	s_nop 1
	v_add_f32_dpp v148, v148, v148 row_mirror row_mask:0xf bank_mask:0xf
	s_nop 1
	v_add_f32_dpp v148, v148, v148 row_bcast:15 row_mask:0xa bank_mask:0xf
	s_nop 1
	v_add_f32_dpp v148, v148, v148 row_bcast:31 row_mask:0xc bank_mask:0xf
	s_nop 0
	v_readlane_b32 s0, v148, 63
	s_nop 0
	v_mov_b32_e32 v148, s0
	v_fmamk_f32 v148, v148, 0x3b000000, v162
	v_mul_f32_e32 v150, 0x4b800000, v148
	v_cmp_gt_f32_e32 vcc, s31, v148
	s_nop 1
	v_cndmask_b32_e32 v148, v148, v150, vcc
	v_rsq_f32_e32 v148, v148
	s_nop 0
	v_mul_f32_e32 v150, 0x45800000, v148
	v_cndmask_b32_e32 v149, v148, v150, vcc
	v_mul_f32_e32 v140, v149, v140
	v_mul_f32_e32 v141, v149, v141
	v_mul_f32_e32 v142, v149, v142
	v_mul_f32_e32 v143, v149, v143
	v_mul_f32_e32 v144, v149, v144
	v_mul_f32_e32 v145, v149, v145
	v_mul_f32_e32 v146, v149, v146
	v_mul_f32_e32 v147, v149, v147
	v_cvt_pk_bf16_f32 v140, v140, v141
	v_cvt_pk_bf16_f32 v141, v142, v143
	v_cvt_pk_bf16_f32 v142, v144, v145
	v_cvt_pk_bf16_f32 v143, v146, v147
	global_store_dwordx4 v[156:157], v[140:143], off offset:2048
	v_lshl_add_u64 v[156:157], v[156:157], 0, s[20:21]
	s_waitcnt vmcnt(10)
	v_lshlrev_b32_e32 v196, 16, v26
	v_and_b32_e32 v197, 0xffff0000, v26
	v_lshlrev_b32_e32 v198, 16, v27
	v_and_b32_e32 v199, 0xffff0000, v27
	v_lshlrev_b32_e32 v200, 16, v28
	v_and_b32_e32 v201, 0xffff0000, v28
	v_lshlrev_b32_e32 v202, 16, v29
	v_and_b32_e32 v203, 0xffff0000, v29
	v_mul_f32_e32 v140, v164, v196
	v_mul_f32_e32 v141, v165, v197
	v_mul_f32_e32 v142, v166, v198
	v_mul_f32_e32 v143, v167, v199
	v_mul_f32_e32 v144, v168, v200
	v_mul_f32_e32 v145, v169, v201
	v_mul_f32_e32 v146, v170, v202
	v_mul_f32_e32 v147, v171, v203
	v_fmac_f32_e32 v140, v172, v188
	v_fmac_f32_e32 v141, v173, v189
	v_fmac_f32_e32 v142, v174, v190
	v_fmac_f32_e32 v143, v175, v191
	v_fmac_f32_e32 v144, v176, v192
	v_fmac_f32_e32 v145, v177, v193
	v_fmac_f32_e32 v146, v178, v194
	v_fmac_f32_e32 v147, v179, v195
	v_fmac_f32_e32 v140, v180, v204
	v_fmac_f32_e32 v141, v181, v205
	v_fmac_f32_e32 v142, v182, v206
	v_fmac_f32_e32 v143, v183, v207
	v_fmac_f32_e32 v144, v184, v208
	v_fmac_f32_e32 v145, v185, v209
	v_fmac_f32_e32 v146, v186, v210
	v_fmac_f32_e32 v147, v187, v211
	v_lshlrev_b32_e32 v150, 16, v10
	v_and_b32_e32 v151, 0xffff0000, v10
	v_mul_f32_e32 v140, v150, v140
	v_mul_f32_e32 v141, v151, v141
	v_lshlrev_b32_e32 v150, 16, v11
	v_and_b32_e32 v151, 0xffff0000, v11
	v_mul_f32_e32 v142, v150, v142
	v_mul_f32_e32 v143, v151, v143
	v_lshlrev_b32_e32 v150, 16, v12
	v_and_b32_e32 v151, 0xffff0000, v12
	v_mul_f32_e32 v144, v150, v144
	v_mul_f32_e32 v145, v151, v145
	v_lshlrev_b32_e32 v150, 16, v13
	v_and_b32_e32 v151, 0xffff0000, v13
	v_mul_f32_e32 v146, v150, v146
	v_mul_f32_e32 v147, v151, v147
	v_mul_f32_e32 v148, v140, v140
	v_fmac_f32_e32 v148, v141, v141
	v_fmac_f32_e32 v148, v142, v142
	v_fmac_f32_e32 v148, v143, v143
	v_fmac_f32_e32 v148, v144, v144
	v_fmac_f32_e32 v148, v145, v145
	v_fmac_f32_e32 v148, v146, v146
	v_fmac_f32_e32 v148, v147, v147
	v_mad_i64_i32 v[152:153], vcc, s41, v221, v[58:59]
	s_add_u32 s41, s41, 1
	global_load_dwordx4 v[10:13], v[152:153], off offset:1536
	global_load_dwordx4 v[26:29], v[152:153], off offset:2560
	s_nop 1
	v_add_f32_dpp v148, v148, v148 quad_perm:[1,0,3,2] row_mask:0xf bank_mask:0xf
	s_nop 1
	v_add_f32_dpp v148, v148, v148 quad_perm:[2,3,0,1] row_mask:0xf bank_mask:0xf
	s_nop 1
	v_add_f32_dpp v148, v148, v148 row_half_mirror row_mask:0xf bank_mask:0xf
	s_nop 1
	v_add_f32_dpp v148, v148, v148 row_mirror row_mask:0xf bank_mask:0xf
	s_nop 1
	v_add_f32_dpp v148, v148, v148 row_bcast:15 row_mask:0xa bank_mask:0xf
	s_nop 1
	v_add_f32_dpp v148, v148, v148 row_bcast:31 row_mask:0xc bank_mask:0xf
	s_nop 0
	v_readlane_b32 s0, v148, 63
	s_nop 0
	v_mov_b32_e32 v148, s0
	v_fmamk_f32 v148, v148, 0x3b000000, v162
	v_mul_f32_e32 v150, 0x4b800000, v148
	v_cmp_gt_f32_e32 vcc, s31, v148
	s_nop 1
	v_cndmask_b32_e32 v148, v148, v150, vcc
	v_rsq_f32_e32 v148, v148
	s_nop 0
	v_mul_f32_e32 v150, 0x45800000, v148
	v_cndmask_b32_e32 v149, v148, v150, vcc
	v_mul_f32_e32 v140, v149, v140
	v_mul_f32_e32 v141, v149, v141
	v_mul_f32_e32 v142, v149, v142
	v_mul_f32_e32 v143, v149, v143
	v_mul_f32_e32 v144, v149, v144
	v_mul_f32_e32 v145, v149, v145
	v_mul_f32_e32 v146, v149, v146
	v_mul_f32_e32 v147, v149, v147
	v_cvt_pk_bf16_f32 v140, v140, v141
	v_cvt_pk_bf16_f32 v141, v142, v143
	v_cvt_pk_bf16_f32 v142, v144, v145
	v_cvt_pk_bf16_f32 v143, v146, v147
	global_store_dwordx4 v[156:157], v[140:143], off
	s_waitcnt vmcnt(10)
; __device__ __forceinline__ unsigned cvt_pk_bf16(float lo, float hi) { unsigned r; asm volatile("v_cvt_pk_bf16_f32 %0, %1, %2" : "=v"(r) : "v"(lo), "v"(hi)); return r; }
; __device__ __forceinline__ float bf_lo(unsigned w) { return __uint_as_float(w << 16); }
; __device__ __forceinline__ float bf_hi(unsigned w) { return __uint_as_float(w & 0xffff0000u); }
; __device__ __forceinline__ float wave_sum(float v) {
; #pragma unroll
;     for (int o = 1; o < 64; o <<= 1) v += __shfl_xor(v, o);
;     return v;
; __global__ void __launch_bounds__(512, 2) trunk_fwd(Args args) {
;     ...
;                     float cv[8], uu[8]; float ss = 0.f;
; #pragma unroll
;                     for (int i = 0; i < 4; ++i) {
;                         uu[2 * i] = bf_lo(gu[i]); uu[2 * i + 1] = bf_hi(gu[i]);
;                         cv[2 * i] = bf_lo(gb[i]) * (w0[2 * i] * uu[2 * i] + w1[2 * i] * u1[2 * i] + w2[2 * i] * u2[2 * i]);
;                         cv[2 * i + 1] = bf_hi(gb[i]) * (w0[2 * i + 1] * uu[2 * i + 1] + w1[2 * i + 1] * u1[2 * i + 1] + w2[2 * i + 1] * u2[2 * i + 1]);
;                     }
; #pragma unroll
;                     for (int i = 0; i < 8; ++i) { ss += cv[i] * cv[i]; u2[i] = u1[i]; u1[i] = uu[i]; }
;                     ss = wave_sum(ss);
;                     const float rc = rsqrtf(ss * (1.0f / 512.0f) + EPS);
;                     u32x4 oc;
; #pragma unroll
;                     for (int i = 0; i < 4; ++i) oc[i] = cvt_pk_bf16(cv[2 * i] * rc, cv[2 * i + 1] * rc);
;                     *(u32x4*)(MIX + (size_t)r * 1024 + 512 + c0) = oc;
	v_lshlrev_b32_e32 v204, 16, v30
	v_and_b32_e32 v205, 0xffff0000, v30
	v_lshlrev_b32_e32 v206, 16, v31
	v_and_b32_e32 v207, 0xffff0000, v31
	v_lshlrev_b32_e32 v208, 16, v32
	v_and_b32_e32 v209, 0xffff0000, v32
	v_lshlrev_b32_e32 v210, 16, v33
	v_and_b32_e32 v211, 0xffff0000, v33
	v_mul_f32_e32 v140, v164, v204
	v_mul_f32_e32 v141, v165, v205
	v_mul_f32_e32 v142, v166, v206
	v_mul_f32_e32 v143, v167, v207
	v_mul_f32_e32 v144, v168, v208
	v_mul_f32_e32 v145, v169, v209
	v_mul_f32_e32 v146, v170, v210
	v_mul_f32_e32 v147, v171, v211
	v_fmac_f32_e32 v140, v172, v196
	v_fmac_f32_e32 v141, v173, v197
	v_fmac_f32_e32 v142, v174, v198
	v_fmac_f32_e32 v143, v175, v199
	v_fmac_f32_e32 v144, v176, v200
	v_fmac_f32_e32 v145, v177, v201
	v_fmac_f32_e32 v146, v178, v202
	v_fmac_f32_e32 v147, v179, v203
	v_fmac_f32_e32 v140, v180, v188
	v_fmac_f32_e32 v141, v181, v189
	v_fmac_f32_e32 v142, v182, v190
	v_fmac_f32_e32 v143, v183, v191
	v_fmac_f32_e32 v144, v184, v192
	v_fmac_f32_e32 v145, v185, v193
	v_fmac_f32_e32 v146, v186, v194
	v_fmac_f32_e32 v147, v187, v195
	v_lshlrev_b32_e32 v150, 16, v14
	v_and_b32_e32 v151, 0xffff0000, v14
	v_mul_f32_e32 v140, v150, v140
	v_mul_f32_e32 v141, v151, v141
	v_lshlrev_b32_e32 v150, 16, v15
	v_and_b32_e32 v151, 0xffff0000, v15
	v_mul_f32_e32 v142, v150, v142
	v_mul_f32_e32 v143, v151, v143
	v_lshlrev_b32_e32 v150, 16, v16
	v_and_b32_e32 v151, 0xffff0000, v16
	v_mul_f32_e32 v144, v150, v144
	v_mul_f32_e32 v145, v151, v145
	v_lshlrev_b32_e32 v150, 16, v17
	v_and_b32_e32 v151, 0xffff0000, v17
	v_mul_f32_e32 v146, v150, v146
	v_mul_f32_e32 v147, v151, v147
	v_mul_f32_e32 v148, v140, v140
	v_fmac_f32_e32 v148, v141, v141
	v_fmac_f32_e32 v148, v142, v142
	v_fmac_f32_e32 v148, v143, v143
	v_fmac_f32_e32 v148, v144, v144
	v_fmac_f32_e32 v148, v145, v145
	v_fmac_f32_e32 v148, v146, v146
	v_fmac_f32_e32 v148, v147, v147
	v_mad_i64_i32 v[152:153], vcc, s41, v221, v[58:59]
	s_add_u32 s41, s41, 1
	global_load_dwordx4 v[14:17], v[152:153], off offset:1536
	global_load_dwordx4 v[30:33], v[152:153], off offset:2560
	s_nop 1
	v_add_f32_dpp v148, v148, v148 quad_perm:[1,0,3,2] row_mask:0xf bank_mask:0xf
	s_nop 1
	v_add_f32_dpp v148, v148, v148 quad_perm:[2,3,0,1] row_mask:0xf bank_mask:0xf
	s_nop 1
	v_add_f32_dpp v148, v148, v148 row_half_mirror row_mask:0xf bank_mask:0xf
	s_nop 1
	v_add_f32_dpp v148, v148, v148 row_mirror row_mask:0xf bank_mask:0xf
	s_nop 1
	v_add_f32_dpp v148, v148, v148 row_bcast:15 row_mask:0xa bank_mask:0xf
	s_nop 1
	v_add_f32_dpp v148, v148, v148 row_bcast:31 row_mask:0xc bank_mask:0xf
	s_nop 0
	v_readlane_b32 s0, v148, 63
	s_nop 0
	v_mov_b32_e32 v148, s0
	v_fmamk_f32 v148, v148, 0x3b000000, v162
	v_mul_f32_e32 v150, 0x4b800000, v148
	v_cmp_gt_f32_e32 vcc, s31, v148
	s_nop 1
	v_cndmask_b32_e32 v148, v148, v150, vcc
	v_rsq_f32_e32 v148, v148
	s_nop 0
	v_mul_f32_e32 v150, 0x45800000, v148
	v_cndmask_b32_e32 v149, v148, v150, vcc
	v_mul_f32_e32 v140, v149, v140
	v_mul_f32_e32 v141, v149, v141
	v_mul_f32_e32 v142, v149, v142
	v_mul_f32_e32 v143, v149, v143
	v_mul_f32_e32 v144, v149, v144
	v_mul_f32_e32 v145, v149, v145
	v_mul_f32_e32 v146, v149, v146
	v_mul_f32_e32 v147, v149, v147
	v_cvt_pk_bf16_f32 v140, v140, v141
	v_cvt_pk_bf16_f32 v141, v142, v143
	v_cvt_pk_bf16_f32 v142, v144, v145
	v_cvt_pk_bf16_f32 v143, v146, v147
	global_store_dwordx4 v[156:157], v[140:143], off offset:2048
	v_lshl_add_u64 v[156:157], v[156:157], 0, s[20:21]
	s_waitcnt vmcnt(10)
	v_lshlrev_b32_e32 v188, 16, v18
	v_and_b32_e32 v189, 0xffff0000, v18
	v_lshlrev_b32_e32 v190, 16, v19
	v_and_b32_e32 v191, 0xffff0000, v19
	v_lshlrev_b32_e32 v192, 16, v20
	v_and_b32_e32 v193, 0xffff0000, v20
	v_lshlrev_b32_e32 v194, 16, v21
	v_and_b32_e32 v195, 0xffff0000, v21
	v_mul_f32_e32 v140, v164, v188
	v_mul_f32_e32 v141, v165, v189
	v_mul_f32_e32 v142, v166, v190
	v_mul_f32_e32 v143, v167, v191
	v_mul_f32_e32 v144, v168, v192
	v_mul_f32_e32 v145, v169, v193
	v_mul_f32_e32 v146, v170, v194
	v_mul_f32_e32 v147, v171, v195
	v_fmac_f32_e32 v140, v172, v204
	v_fmac_f32_e32 v141, v173, v205
	v_fmac_f32_e32 v142, v174, v206
	v_fmac_f32_e32 v143, v175, v207
	v_fmac_f32_e32 v144, v176, v208
	v_fmac_f32_e32 v145, v177, v209
	v_fmac_f32_e32 v146, v178, v210
	v_fmac_f32_e32 v147, v179, v211
	v_fmac_f32_e32 v140, v180, v196
	v_fmac_f32_e32 v141, v181, v197
	v_fmac_f32_e32 v142, v182, v198
	v_fmac_f32_e32 v143, v183, v199
	v_fmac_f32_e32 v144, v184, v200
	v_fmac_f32_e32 v145, v185, v201
	v_fmac_f32_e32 v146, v186, v202
	v_fmac_f32_e32 v147, v187, v203
	v_lshlrev_b32_e32 v150, 16, v2
	v_and_b32_e32 v151, 0xffff0000, v2
	v_mul_f32_e32 v140, v150, v140
	v_mul_f32_e32 v141, v151, v141
	v_lshlrev_b32_e32 v150, 16, v3
	v_and_b32_e32 v151, 0xffff0000, v3
	v_mul_f32_e32 v142, v150, v142
	v_mul_f32_e32 v143, v151, v143
	v_lshlrev_b32_e32 v150, 16, v4
	v_and_b32_e32 v151, 0xffff0000, v4
	v_mul_f32_e32 v144, v150, v144
	v_mul_f32_e32 v145, v151, v145
	v_lshlrev_b32_e32 v150, 16, v5
	v_and_b32_e32 v151, 0xffff0000, v5
	v_mul_f32_e32 v146, v150, v146
	v_mul_f32_e32 v147, v151, v147
	v_mul_f32_e32 v148, v140, v140
	v_fmac_f32_e32 v148, v141, v141
	v_fmac_f32_e32 v148, v142, v142
	v_fmac_f32_e32 v148, v143, v143
	v_fmac_f32_e32 v148, v144, v144
	v_fmac_f32_e32 v148, v145, v145
	v_fmac_f32_e32 v148, v146, v146
	v_fmac_f32_e32 v148, v147, v147
	s_nop 1
	v_add_f32_dpp v148, v148, v148 quad_perm:[1,0,3,2] row_mask:0xf bank_mask:0xf
	s_nop 1
	v_add_f32_dpp v148, v148, v148 quad_perm:[2,3,0,1] row_mask:0xf bank_mask:0xf
	s_nop 1
	v_add_f32_dpp v148, v148, v148 row_half_mirror row_mask:0xf bank_mask:0xf
	s_nop 1
	v_add_f32_dpp v148, v148, v148 row_mirror row_mask:0xf bank_mask:0xf
	s_nop 1
	v_add_f32_dpp v148, v148, v148 row_bcast:15 row_mask:0xa bank_mask:0xf
	s_nop 1
	v_add_f32_dpp v148, v148, v148 row_bcast:31 row_mask:0xc bank_mask:0xf
	s_nop 0
	v_readlane_b32 s0, v148, 63
	s_nop 0
	v_mov_b32_e32 v148, s0
	v_fmamk_f32 v148, v148, 0x3b000000, v162
	v_mul_f32_e32 v150, 0x4b800000, v148
	v_cmp_gt_f32_e32 vcc, s31, v148
	s_nop 1
	v_cndmask_b32_e32 v148, v148, v150, vcc
	v_rsq_f32_e32 v148, v148
	s_nop 0
	v_mul_f32_e32 v150, 0x45800000, v148
	v_cndmask_b32_e32 v149, v148, v150, vcc
	v_mul_f32_e32 v140, v149, v140
	v_mul_f32_e32 v141, v149, v141
	v_mul_f32_e32 v142, v149, v142
	v_mul_f32_e32 v143, v149, v143
	v_mul_f32_e32 v144, v149, v144
	v_mul_f32_e32 v145, v149, v145
	v_mul_f32_e32 v146, v149, v146
	v_mul_f32_e32 v147, v149, v147
	v_cvt_pk_bf16_f32 v140, v140, v141
	v_cvt_pk_bf16_f32 v141, v142, v143
	v_cvt_pk_bf16_f32 v142, v144, v145
	v_cvt_pk_bf16_f32 v143, v146, v147
	global_store_dwordx4 v[156:157], v[140:143], off
	s_waitcnt vmcnt(8)
; __device__ __forceinline__ unsigned cvt_pk_bf16(float lo, float hi) { unsigned r; asm volatile("v_cvt_pk_bf16_f32 %0, %1, %2" : "=v"(r) : "v"(lo), "v"(hi)); return r; }
; __device__ __forceinline__ float bf_lo(unsigned w) { return __uint_as_float(w << 16); }
; __device__ __forceinline__ float bf_hi(unsigned w) { return __uint_as_float(w & 0xffff0000u); }
; __device__ __forceinline__ float wave_sum(float v) {
; #pragma unroll
;     for (int o = 1; o < 64; o <<= 1) v += __shfl_xor(v, o);
;     return v;
; __global__ void __launch_bounds__(512, 2) trunk_fwd(Args args) {
;     ...
;                     float cv[8], uu[8]; float ss = 0.f;
; #pragma unroll
;                     for (int i = 0; i < 4; ++i) {
;                         uu[2 * i] = bf_lo(gu[i]); uu[2 * i + 1] = bf_hi(gu[i]);
;                         cv[2 * i] = bf_lo(gb[i]) * (w0[2 * i] * uu[2 * i] + w1[2 * i] * u1[2 * i] + w2[2 * i] * u2[2 * i]);
;                         cv[2 * i + 1] = bf_hi(gb[i]) * (w0[2 * i + 1] * uu[2 * i + 1] + w1[2 * i + 1] * u1[2 * i + 1] + w2[2 * i + 1] * u2[2 * i + 1]);
;                     }
; #pragma unroll
;                     for (int i = 0; i < 8; ++i) { ss += cv[i] * cv[i]; u2[i] = u1[i]; u1[i] = uu[i]; }
;                     ss = wave_sum(ss);
;                     const float rc = rsqrtf(ss * (1.0f / 512.0f) + EPS);
;                     u32x4 oc;
; #pragma unroll
;                     for (int i = 0; i < 4; ++i) oc[i] = cvt_pk_bf16(cv[2 * i] * rc, cv[2 * i + 1] * rc);
;                     *(u32x4*)(MIX + (size_t)r * 1024 + 512 + c0) = oc;
	v_lshlrev_b32_e32 v196, 16, v22
	v_and_b32_e32 v197, 0xffff0000, v22
	v_lshlrev_b32_e32 v198, 16, v23
	v_and_b32_e32 v199, 0xffff0000, v23
	v_lshlrev_b32_e32 v200, 16, v24
	v_and_b32_e32 v201, 0xffff0000, v24
	v_lshlrev_b32_e32 v202, 16, v25
	v_and_b32_e32 v203, 0xffff0000, v25
	v_mul_f32_e32 v140, v164, v196
	v_mul_f32_e32 v141, v165, v197
	v_mul_f32_e32 v142, v166, v198
	v_mul_f32_e32 v143, v167, v199
	v_mul_f32_e32 v144, v168, v200
	v_mul_f32_e32 v145, v169, v201
	v_mul_f32_e32 v146, v170, v202
	v_mul_f32_e32 v147, v171, v203
	v_fmac_f32_e32 v140, v172, v188
	v_fmac_f32_e32 v141, v173, v189
	v_fmac_f32_e32 v142, v174, v190
	v_fmac_f32_e32 v143, v175, v191
	v_fmac_f32_e32 v144, v176, v192
	v_fmac_f32_e32 v145, v177, v193
	v_fmac_f32_e32 v146, v178, v194
	v_fmac_f32_e32 v147, v179, v195
	v_fmac_f32_e32 v140, v180, v204
	v_fmac_f32_e32 v141, v181, v205
	v_fmac_f32_e32 v142, v182, v206
	v_fmac_f32_e32 v143, v183, v207
	v_fmac_f32_e32 v144, v184, v208
	v_fmac_f32_e32 v145, v185, v209
	v_fmac_f32_e32 v146, v186, v210
	v_fmac_f32_e32 v147, v187, v211
	v_lshlrev_b32_e32 v150, 16, v6
	v_and_b32_e32 v151, 0xffff0000, v6
	v_mul_f32_e32 v140, v150, v140
	v_mul_f32_e32 v141, v151, v141
	v_lshlrev_b32_e32 v150, 16, v7
	v_and_b32_e32 v151, 0xffff0000, v7
	v_mul_f32_e32 v142, v150, v142
	v_mul_f32_e32 v143, v151, v143
	v_lshlrev_b32_e32 v150, 16, v8
	v_and_b32_e32 v151, 0xffff0000, v8
	v_mul_f32_e32 v144, v150, v144
	v_mul_f32_e32 v145, v151, v145
	v_lshlrev_b32_e32 v150, 16, v9
	v_and_b32_e32 v151, 0xffff0000, v9
	v_mul_f32_e32 v146, v150, v146
	v_mul_f32_e32 v147, v151, v147
	v_mul_f32_e32 v148, v140, v140
	v_fmac_f32_e32 v148, v141, v141
	v_fmac_f32_e32 v148, v142, v142
	v_fmac_f32_e32 v148, v143, v143
	v_fmac_f32_e32 v148, v144, v144
	v_fmac_f32_e32 v148, v145, v145
	v_fmac_f32_e32 v148, v146, v146
	v_fmac_f32_e32 v148, v147, v147
	s_nop 1
	v_add_f32_dpp v148, v148, v148 quad_perm:[1,0,3,2] row_mask:0xf bank_mask:0xf
	s_nop 1
	v_add_f32_dpp v148, v148, v148 quad_perm:[2,3,0,1] row_mask:0xf bank_mask:0xf
	s_nop 1
	v_add_f32_dpp v148, v148, v148 row_half_mirror row_mask:0xf bank_mask:0xf
	s_nop 1
	v_add_f32_dpp v148, v148, v148 row_mirror row_mask:0xf bank_mask:0xf
	s_nop 1
	v_add_f32_dpp v148, v148, v148 row_bcast:15 row_mask:0xa bank_mask:0xf
	s_nop 1
	v_add_f32_dpp v148, v148, v148 row_bcast:31 row_mask:0xc bank_mask:0xf
	s_nop 0
	v_readlane_b32 s0, v148, 63
	s_nop 0
	v_mov_b32_e32 v148, s0
	v_fmamk_f32 v148, v148, 0x3b000000, v162
	v_mul_f32_e32 v150, 0x4b800000, v148
	v_cmp_gt_f32_e32 vcc, s31, v148
	s_nop 1
	v_cndmask_b32_e32 v148, v148, v150, vcc
	v_rsq_f32_e32 v148, v148
	s_nop 0
	v_mul_f32_e32 v150, 0x45800000, v148
	v_cndmask_b32_e32 v149, v148, v150, vcc
	v_mul_f32_e32 v140, v149, v140
	v_mul_f32_e32 v141, v149, v141
	v_mul_f32_e32 v142, v149, v142
	v_mul_f32_e32 v143, v149, v143
	v_mul_f32_e32 v144, v149, v144
	v_mul_f32_e32 v145, v149, v145
	v_mul_f32_e32 v146, v149, v146
	v_mul_f32_e32 v147, v149, v147
	v_cvt_pk_bf16_f32 v140, v140, v141
	v_cvt_pk_bf16_f32 v141, v142, v143
	v_cvt_pk_bf16_f32 v142, v144, v145
	v_cvt_pk_bf16_f32 v143, v146, v147
	global_store_dwordx4 v[156:157], v[140:143], off offset:2048
	v_lshl_add_u64 v[156:157], v[156:157], 0, s[20:21]
	s_waitcnt vmcnt(6)
	v_lshlrev_b32_e32 v204, 16, v26
	v_and_b32_e32 v205, 0xffff0000, v26
	v_lshlrev_b32_e32 v206, 16, v27
	v_and_b32_e32 v207, 0xffff0000, v27
	v_lshlrev_b32_e32 v208, 16, v28
	v_and_b32_e32 v209, 0xffff0000, v28
	v_lshlrev_b32_e32 v210, 16, v29
	v_and_b32_e32 v211, 0xffff0000, v29
	v_mul_f32_e32 v140, v164, v204
	v_mul_f32_e32 v141, v165, v205
	v_mul_f32_e32 v142, v166, v206
	v_mul_f32_e32 v143, v167, v207
	v_mul_f32_e32 v144, v168, v208
	v_mul_f32_e32 v145, v169, v209
	v_mul_f32_e32 v146, v170, v210
	v_mul_f32_e32 v147, v171, v211
	v_fmac_f32_e32 v140, v172, v196
	v_fmac_f32_e32 v141, v173, v197
	v_fmac_f32_e32 v142, v174, v198
	v_fmac_f32_e32 v143, v175, v199
	v_fmac_f32_e32 v144, v176, v200
	v_fmac_f32_e32 v145, v177, v201
	v_fmac_f32_e32 v146, v178, v202
	v_fmac_f32_e32 v147, v179, v203
	v_fmac_f32_e32 v140, v180, v188
	v_fmac_f32_e32 v141, v181, v189
	v_fmac_f32_e32 v142, v182, v190
	v_fmac_f32_e32 v143, v183, v191
	v_fmac_f32_e32 v144, v184, v192
	v_fmac_f32_e32 v145, v185, v193
	v_fmac_f32_e32 v146, v186, v194
	v_fmac_f32_e32 v147, v187, v195
	v_lshlrev_b32_e32 v150, 16, v10
	v_and_b32_e32 v151, 0xffff0000, v10
	v_mul_f32_e32 v140, v150, v140
	v_mul_f32_e32 v141, v151, v141
	v_lshlrev_b32_e32 v150, 16, v11
	v_and_b32_e32 v151, 0xffff0000, v11
	v_mul_f32_e32 v142, v150, v142
	v_mul_f32_e32 v143, v151, v143
	v_lshlrev_b32_e32 v150, 16, v12
	v_and_b32_e32 v151, 0xffff0000, v12
	v_mul_f32_e32 v144, v150, v144
	v_mul_f32_e32 v145, v151, v145
	v_lshlrev_b32_e32 v150, 16, v13
	v_and_b32_e32 v151, 0xffff0000, v13
	v_mul_f32_e32 v146, v150, v146
	v_mul_f32_e32 v147, v151, v147
	v_mul_f32_e32 v148, v140, v140
	v_fmac_f32_e32 v148, v141, v141
	v_fmac_f32_e32 v148, v142, v142
	v_fmac_f32_e32 v148, v143, v143
	v_fmac_f32_e32 v148, v144, v144
	v_fmac_f32_e32 v148, v145, v145
	v_fmac_f32_e32 v148, v146, v146
	v_fmac_f32_e32 v148, v147, v147
	s_nop 1
	v_add_f32_dpp v148, v148, v148 quad_perm:[1,0,3,2] row_mask:0xf bank_mask:0xf
	s_nop 1
	v_add_f32_dpp v148, v148, v148 quad_perm:[2,3,0,1] row_mask:0xf bank_mask:0xf
	s_nop 1
	v_add_f32_dpp v148, v148, v148 row_half_mirror row_mask:0xf bank_mask:0xf
	s_nop 1
	v_add_f32_dpp v148, v148, v148 row_mirror row_mask:0xf bank_mask:0xf
	s_nop 1
	v_add_f32_dpp v148, v148, v148 row_bcast:15 row_mask:0xa bank_mask:0xf
	s_nop 1
	v_add_f32_dpp v148, v148, v148 row_bcast:31 row_mask:0xc bank_mask:0xf
	s_nop 0
	v_readlane_b32 s0, v148, 63
	s_nop 0
	v_mov_b32_e32 v148, s0
	v_fmamk_f32 v148, v148, 0x3b000000, v162
	v_mul_f32_e32 v150, 0x4b800000, v148
	v_cmp_gt_f32_e32 vcc, s31, v148
	s_nop 1
	v_cndmask_b32_e32 v148, v148, v150, vcc
	v_rsq_f32_e32 v148, v148
	s_nop 0
	v_mul_f32_e32 v150, 0x45800000, v148
	v_cndmask_b32_e32 v149, v148, v150, vcc
	v_mul_f32_e32 v140, v149, v140
	v_mul_f32_e32 v141, v149, v141
	v_mul_f32_e32 v142, v149, v142
	v_mul_f32_e32 v143, v149, v143
	v_mul_f32_e32 v144, v149, v144
	v_mul_f32_e32 v145, v149, v145
	v_mul_f32_e32 v146, v149, v146
	v_mul_f32_e32 v147, v149, v147
	v_cvt_pk_bf16_f32 v140, v140, v141
	v_cvt_pk_bf16_f32 v141, v142, v143
	v_cvt_pk_bf16_f32 v142, v144, v145
	v_cvt_pk_bf16_f32 v143, v146, v147
	global_store_dwordx4 v[156:157], v[140:143], off
	s_waitcnt vmcnt(4)
; __device__ __forceinline__ unsigned cvt_pk_bf16(float lo, float hi) { unsigned r; asm volatile("v_cvt_pk_bf16_f32 %0, %1, %2" : "=v"(r) : "v"(lo), "v"(hi)); return r; }
; __device__ __forceinline__ float bf_lo(unsigned w) { return __uint_as_float(w << 16); }
; __device__ __forceinline__ float bf_hi(unsigned w) { return __uint_as_float(w & 0xffff0000u); }
; __device__ __forceinline__ float wave_sum(float v) {
; #pragma unroll
;     for (int o = 1; o < 64; o <<= 1) v += __shfl_xor(v, o);
;     return v;
; __global__ void __launch_bounds__(512, 2) trunk_fwd(Args args) {
;     ...
;                     float cv[8], uu[8]; float ss = 0.f;
; #pragma unroll
;                     for (int i = 0; i < 4; ++i) {
;                         uu[2 * i] = bf_lo(gu[i]); uu[2 * i + 1] = bf_hi(gu[i]);
;                         cv[2 * i] = bf_lo(gb[i]) * (w0[2 * i] * uu[2 * i] + w1[2 * i] * u1[2 * i] + w2[2 * i] * u2[2 * i]);
;                         cv[2 * i + 1] = bf_hi(gb[i]) * (w0[2 * i + 1] * uu[2 * i + 1] + w1[2 * i + 1] * u1[2 * i + 1] + w2[2 * i + 1] * u2[2 * i + 1]);
;                     }
; #pragma unroll
;                     for (int i = 0; i < 8; ++i) { ss += cv[i] * cv[i]; u2[i] = u1[i]; u1[i] = uu[i]; }
;                     ss = wave_sum(ss);
;                     const float rc = rsqrtf(ss * (1.0f / 512.0f) + EPS);
;                     u32x4 oc;
; #pragma unroll
;                     for (int i = 0; i < 4; ++i) oc[i] = cvt_pk_bf16(cv[2 * i] * rc, cv[2 * i + 1] * rc);
;                     *(u32x4*)(MIX + (size_t)r * 1024 + 512 + c0) = oc;
	v_lshlrev_b32_e32 v188, 16, v30
	v_and_b32_e32 v189, 0xffff0000, v30
	v_lshlrev_b32_e32 v190, 16, v31
	v_and_b32_e32 v191, 0xffff0000, v31
	v_lshlrev_b32_e32 v192, 16, v32
	v_and_b32_e32 v193, 0xffff0000, v32
	v_lshlrev_b32_e32 v194, 16, v33
	v_and_b32_e32 v195, 0xffff0000, v33
	v_mul_f32_e32 v140, v164, v188
	v_mul_f32_e32 v141, v165, v189
	v_mul_f32_e32 v142, v166, v190
	v_mul_f32_e32 v143, v167, v191
	v_mul_f32_e32 v144, v168, v192
	v_mul_f32_e32 v145, v169, v193
	v_mul_f32_e32 v146, v170, v194
	v_mul_f32_e32 v147, v171, v195
	v_fmac_f32_e32 v140, v172, v204
	v_fmac_f32_e32 v141, v173, v205
	v_fmac_f32_e32 v142, v174, v206
	v_fmac_f32_e32 v143, v175, v207
	v_fmac_f32_e32 v144, v176, v208
	v_fmac_f32_e32 v145, v177, v209
	v_fmac_f32_e32 v146, v178, v210
	v_fmac_f32_e32 v147, v179, v211
	v_fmac_f32_e32 v140, v180, v196
	v_fmac_f32_e32 v141, v181, v197
	v_fmac_f32_e32 v142, v182, v198
	v_fmac_f32_e32 v143, v183, v199
	v_fmac_f32_e32 v144, v184, v200
	v_fmac_f32_e32 v145, v185, v201
	v_fmac_f32_e32 v146, v186, v202
	v_fmac_f32_e32 v147, v187, v203
	v_lshlrev_b32_e32 v150, 16, v14
	v_and_b32_e32 v151, 0xffff0000, v14
	v_mul_f32_e32 v140, v150, v140
	v_mul_f32_e32 v141, v151, v141
	v_lshlrev_b32_e32 v150, 16, v15
	v_and_b32_e32 v151, 0xffff0000, v15
	v_mul_f32_e32 v142, v150, v142
	v_mul_f32_e32 v143, v151, v143
	v_lshlrev_b32_e32 v150, 16, v16
	v_and_b32_e32 v151, 0xffff0000, v16
	v_mul_f32_e32 v144, v150, v144
	v_mul_f32_e32 v145, v151, v145
	v_lshlrev_b32_e32 v150, 16, v17
	v_and_b32_e32 v151, 0xffff0000, v17
	v_mul_f32_e32 v146, v150, v146
	v_mul_f32_e32 v147, v151, v147
	v_mul_f32_e32 v148, v140, v140
	v_fmac_f32_e32 v148, v141, v141
	v_fmac_f32_e32 v148, v142, v142
	v_fmac_f32_e32 v148, v143, v143
	v_fmac_f32_e32 v148, v144, v144
	v_fmac_f32_e32 v148, v145, v145
	v_fmac_f32_e32 v148, v146, v146
	v_fmac_f32_e32 v148, v147, v147
	s_nop 1
	v_add_f32_dpp v148, v148, v148 quad_perm:[1,0,3,2] row_mask:0xf bank_mask:0xf
	s_nop 1
	v_add_f32_dpp v148, v148, v148 quad_perm:[2,3,0,1] row_mask:0xf bank_mask:0xf
	s_nop 1
	v_add_f32_dpp v148, v148, v148 row_half_mirror row_mask:0xf bank_mask:0xf
	s_nop 1
	v_add_f32_dpp v148, v148, v148 row_mirror row_mask:0xf bank_mask:0xf
	s_nop 1
	v_add_f32_dpp v148, v148, v148 row_bcast:15 row_mask:0xa bank_mask:0xf
	s_nop 1
	v_add_f32_dpp v148, v148, v148 row_bcast:31 row_mask:0xc bank_mask:0xf
	s_nop 0
	v_readlane_b32 s0, v148, 63
	s_nop 0
	v_mov_b32_e32 v148, s0
	v_fmamk_f32 v148, v148, 0x3b000000, v162
	v_mul_f32_e32 v150, 0x4b800000, v148
	v_cmp_gt_f32_e32 vcc, s31, v148
	s_nop 1
	v_cndmask_b32_e32 v148, v148, v150, vcc
	v_rsq_f32_e32 v148, v148
	s_nop 0
	v_mul_f32_e32 v150, 0x45800000, v148
	v_cndmask_b32_e32 v149, v148, v150, vcc
	v_mul_f32_e32 v140, v149, v140
	v_mul_f32_e32 v141, v149, v141
	v_mul_f32_e32 v142, v149, v142
	v_mul_f32_e32 v143, v149, v143
	v_mul_f32_e32 v144, v149, v144
	v_mul_f32_e32 v145, v149, v145
	v_mul_f32_e32 v146, v149, v146
	v_mul_f32_e32 v147, v149, v147
	v_cvt_pk_bf16_f32 v140, v140, v141
	v_cvt_pk_bf16_f32 v141, v142, v143
	v_cvt_pk_bf16_f32 v142, v144, v145
	v_cvt_pk_bf16_f32 v143, v146, v147
	global_store_dwordx4 v[156:157], v[140:143], off offset:2048
	v_lshl_add_u64 v[156:157], v[156:157], 0, s[20:21]
	s_branch .LBB0_1053
